# v37 + xbc conv-weight prefetch in GEMM1 epilogue + attention O stores widened via LDS transpose (8x dwordx4 instead of 64x short)
# baseline (speedup 1.0000x reference)
; __device__ __forceinline__ unsigned cvt_pk_bf16(float lo, float hi) { unsigned r; asm volatile("v_cvt_pk_bf16_f32 %0, %1, %2" : "=v"(r) : "v"(lo), "v"(hi)); return r; }
; __device__ __forceinline__ float epi_sigmoid(float v) { return __builtin_amdgcn_rcpf(1.0f + __expf(-v)); }
; __device__ __forceinline__ f32x4 dpp_prev4(const f32x4& v) { return (f32x4){dpp_prev(v[0]), dpp_prev(v[1]), dpp_prev(v[2]), dpp_prev(v[3])}; }
; __device__ __forceinline__ f32x4 dpp_next4(const f32x4& v) { return (f32x4){dpp_next(v[0]), dpp_next(v[1]), dpp_next(v[2]), dpp_next(v[3])}; }
;     __device__ __forceinline__ void operator()(const f32x4 (&acc)[2][2][4][2], const Unit& u, int wr, int wc, int fr, int fq) const {
;     ...
;         if (pn >= 32 && pn < 72) {
;             const int seg = 2 * u.pm + wr;
; #pragma unroll
;             for (int bj = 0; bj < 2; ++bj)
; #pragma unroll
;                 for (int n = 0; n < 2; ++n) {
;                     const int ch = (pn - 32) * 256 + bj * HALF + cw_ + 4 * n;
;                     const f32x4 w0 = *(const f32x4*)(cw + ch), w1 = *(const f32x4*)(cw + 10240 + ch), w2 = *(const f32x4*)(cw + 2 * 10240 + ch), bb = *(const f32x4*)(cb + ch);
; #pragma unroll
;                     for (int kk = 0; kk < 8; ++kk) {
;                         const f32x4 um = (kk == 0) ? dpp_prev4(acc[1][bj][3][n]) : acc[(kk - 1) >> 2][bj][(kk - 1) & 3][n], up = (kk == 7) ? dpp_next4(acc[0][bj][0][n]) : acc[(kk + 1) >> 2][bj][(kk + 1) & 3][n];
;                         const f32x4 c4 = um * w0 + acc[kk >> 2][bj][kk & 3][n] * w1 + up * w2 + bb;
;                         typedef unsigned u32x2_ __attribute__((ext_vector_type(2)));
;                         u32x2_ w; w.x = cvt_pk_bf16(c4[0] * epi_sigmoid(c4[0]), c4[1] * epi_sigmoid(c4[1])); w.y = cvt_pk_bf16(c4[2] * epi_sigmoid(c4[2]), c4[3] * epi_sigmoid(c4[3]));
;                         *(u32x2_*)(xbc + (size_t)(row0 + kk) * 10240 + ch) = w;
.LBB0_190:
	s_and_b64 vcc, exec, s[4:5]
	s_cbranch_vccz .LBB0_224
	v_lshl_add_u32 v152, s40, 8, v199
	v_readlane_b32 s40, v254, 0
	v_lshlrev_b64 v[112:113], 2, v[152:153]
	v_readlane_b32 s50, v254, 10
	v_readlane_b32 s51, v254, 11
	v_lshl_add_u64 v[114:115], s[26:27], 0, v[112:113]
	v_readlane_b32 s52, v254, 12
	v_lshl_add_u64 v[174:175], s[50:51], 0, v[112:113]
	global_load_dwordx4 v[136:139], v[174:175], off
	global_load_dwordx4 v[140:143], v[114:115], off
	v_readlane_b32 s53, v254, 13
	v_lshl_add_u64 v[114:115], s[28:29], 0, v[112:113]
	global_load_dwordx4 v[116:119], v[114:115], off
	v_lshl_add_u64 v[176:177], s[52:53], 0, v[112:113]
	v_lshl_add_u64 v[244:245], s[26:27], 0, v[112:113]
	v_lshl_add_u64 v[246:247], s[28:29], 0, v[112:113]
	global_load_dwordx4 v[212:215], v[174:175], off offset:16
	global_load_dwordx4 v[216:219], v[244:245], off offset:16
	global_load_dwordx4 v[220:223], v[246:247], off offset:16
	global_load_dwordx4 v[224:227], v[176:177], off offset:16
	global_load_dwordx4 v[228:231], v[174:175], off offset:512
	global_load_dwordx4 v[232:235], v[244:245], off offset:512
	global_load_dwordx4 v[236:239], v[246:247], off offset:512
	global_load_dwordx4 v[240:243], v[176:177], off offset:512
	global_load_dwordx4 v[112:115], v[176:177], off
	v_mov_b32_dpp v178, v68 row_shr:1 row_mask:0xf bank_mask:0xf bound_ctrl:1
	v_mov_b32_dpp v179, v69 row_shr:1 row_mask:0xf bank_mask:0xf bound_ctrl:1
	v_mov_b32_dpp v180, v70 row_shr:1 row_mask:0xf bank_mask:0xf bound_ctrl:1
	v_mov_b32_dpp v181, v71 row_shr:1 row_mask:0xf bank_mask:0xf bound_ctrl:1
	v_mov_b64_e32 v[188:189], s[12:13]
	v_lshlrev_b64 v[194:195], 1, v[152:153]
	v_mov_b32_dpp v210, v134 row_shl:1 row_mask:0xf bank_mask:0xf bound_ctrl:1
	v_mov_b32_dpp v211, v135 row_shl:1 row_mask:0xf bank_mask:0xf bound_ctrl:1
	s_lshl_b32 s0, s0, 1
	s_add_i32 s31, s0, s69
	v_readlane_b32 s41, v254, 1
	s_mul_hi_i32 s19, s31, 0x28000
	s_mul_i32 s31, s31, 0x28000
	v_cmp_lt_i32_e32 vcc, 14, v196
	s_mov_b64 s[0:1], 0
	v_readlane_b32 s42, v254, 2
	v_readlane_b32 s43, v254, 3
	v_readlane_b32 s44, v254, 4
	v_readlane_b32 s45, v254, 5
	v_readlane_b32 s46, v254, 6
	v_readlane_b32 s47, v254, 7
	v_readlane_b32 s48, v254, 8
	v_readlane_b32 s49, v254, 9
	v_readlane_b32 s54, v254, 14
	v_readlane_b32 s55, v254, 15
	s_waitcnt vmcnt(0)
	v_pk_mul_f32 v[178:179], v[136:137], v[178:179]
	s_nop 0
	v_pk_fma_f32 v[178:179], v[132:133], v[140:141], v[178:179]
	v_pk_mul_f32 v[180:181], v[138:139], v[180:181]
	v_pk_mul_f32 v[182:183], v[100:101], v[140:141]
	v_pk_fma_f32 v[178:179], v[124:125], v[116:117], v[178:179]
	v_pk_fma_f32 v[180:181], v[134:135], v[142:143], v[180:181]
	v_pk_add_f32 v[178:179], v[112:113], v[178:179]
	v_pk_fma_f32 v[180:181], v[126:127], v[118:119], v[180:181]
	v_mul_f32_e32 v169, 0xbfb8aa3b, v178
	v_mul_f32_e32 v171, 0xbfb8aa3b, v179
	v_exp_f32_e32 v169, v169
	v_exp_f32_e32 v171, v171
	v_pk_add_f32 v[180:181], v[114:115], v[180:181]
	v_pk_fma_f32 v[182:183], v[108:109], v[136:137], v[182:183]
	v_add_f32_e32 v169, 1.0, v169
	v_add_f32_e32 v171, 1.0, v171
	v_rcp_f32_e32 v169, v169
	v_rcp_f32_e32 v171, v171
	v_pk_fma_f32 v[182:183], v[92:93], v[116:117], v[182:183]
	v_pk_mul_f32 v[184:185], v[92:93], v[140:141]
	v_mul_f32_e32 v169, v178, v169
	v_mul_f32_e32 v171, v179, v171
	v_cvt_pk_bf16_f32 v178, v169, v171
	v_mul_f32_e32 v169, 0xbfb8aa3b, v180
	v_mul_f32_e32 v171, 0xbfb8aa3b, v181
	v_exp_f32_e32 v169, v169
	v_exp_f32_e32 v171, v171
	v_pk_add_f32 v[182:183], v[112:113], v[182:183]
	v_pk_fma_f32 v[184:185], v[100:101], v[136:137], v[184:185]
	v_add_f32_e32 v169, 1.0, v169
	v_add_f32_e32 v171, 1.0, v171
	v_rcp_f32_e32 v169, v169
	v_rcp_f32_e32 v171, v171
	v_pk_fma_f32 v[184:185], v[84:85], v[116:117], v[184:185]
	v_pk_mul_f32 v[186:187], v[84:85], v[140:141]
	v_mul_f32_e32 v169, v180, v169
	v_mul_f32_e32 v171, v181, v171
	v_mad_i64_i32 v[180:181], s[4:5], v172, s93, v[188:189]
	v_lshl_add_u64 v[190:191], v[180:181], 0, v[194:195]
	v_pk_mul_f32 v[180:181], v[124:125], v[140:141]
	v_cvt_pk_bf16_f32 v179, v169, v171
	global_store_dwordx2 v[190:191], v[178:179], off
	v_pk_fma_f32 v[180:181], v[132:133], v[136:137], v[180:181]
	v_pk_mul_f32 v[178:179], v[126:127], v[142:143]
	v_pk_fma_f32 v[180:181], v[108:109], v[116:117], v[180:181]
	v_pk_fma_f32 v[178:179], v[134:135], v[138:139], v[178:179]
	v_pk_add_f32 v[180:181], v[112:113], v[180:181]
	v_pk_fma_f32 v[178:179], v[110:111], v[118:119], v[178:179]
	v_mul_f32_e32 v169, 0xbfb8aa3b, v180
	v_exp_f32_e32 v169, v169
	v_mul_f32_e32 v171, 0xbfb8aa3b, v181
	v_exp_f32_e32 v171, v171
	v_pk_add_f32 v[178:179], v[114:115], v[178:179]
	v_add_f32_e32 v169, 1.0, v169
	v_rcp_f32_e32 v169, v169
	v_add_f32_e32 v171, 1.0, v171
	v_rcp_f32_e32 v171, v171
	v_pk_add_f32 v[184:185], v[112:113], v[184:185]
	v_mul_f32_e32 v169, v180, v169
	v_pk_fma_f32 v[186:187], v[92:93], v[136:137], v[186:187]
	v_mul_f32_e32 v171, v181, v171
	v_cvt_pk_bf16_f32 v180, v169, v171
	v_mul_f32_e32 v169, 0xbfb8aa3b, v178
	v_exp_f32_e32 v169, v169
	v_mul_f32_e32 v171, 0xbfb8aa3b, v179
	v_exp_f32_e32 v171, v171
	v_pk_fma_f32 v[186:187], v[76:77], v[116:117], v[186:187]
	v_add_f32_e32 v169, 1.0, v169
	v_rcp_f32_e32 v169, v169
	v_add_f32_e32 v171, 1.0, v171
	v_rcp_f32_e32 v171, v171
	v_pk_add_f32 v[186:187], v[112:113], v[186:187]
	v_mul_f32_e32 v169, v178, v169
	v_pk_mul_f32 v[208:209], v[76:77], v[140:141]
	v_mul_f32_e32 v171, v179, v171
	v_cvt_pk_bf16_f32 v181, v169, v171
	v_or_b32_e32 v169, 1, v172
	v_mad_i64_i32 v[178:179], s[4:5], v169, s93, v[188:189]
	v_lshl_add_u64 v[192:193], v[178:179], 0, v[194:195]
	global_store_dwordx2 v[192:193], v[180:181], off
	v_pk_mul_f32 v[180:181], v[108:109], v[140:141]
; __device__ __forceinline__ unsigned cvt_pk_bf16(float lo, float hi) { unsigned r; asm volatile("v_cvt_pk_bf16_f32 %0, %1, %2" : "=v"(r) : "v"(lo), "v"(hi)); return r; }
; __device__ __forceinline__ float epi_sigmoid(float v) { return __builtin_amdgcn_rcpf(1.0f + __expf(-v)); }
; __device__ __forceinline__ f32x4 dpp_prev4(const f32x4& v) { return (f32x4){dpp_prev(v[0]), dpp_prev(v[1]), dpp_prev(v[2]), dpp_prev(v[3])}; }
; __device__ __forceinline__ f32x4 dpp_next4(const f32x4& v) { return (f32x4){dpp_next(v[0]), dpp_next(v[1]), dpp_next(v[2]), dpp_next(v[3])}; }
;     __device__ __forceinline__ void operator()(const f32x4 (&acc)[2][2][4][2], const Unit& u, int wr, int wc, int fr, int fq) const {
;     ...
;                     for (int kk = 0; kk < 8; ++kk) {
;                         const f32x4 um = (kk == 0) ? dpp_prev4(acc[1][bj][3][n]) : acc[(kk - 1) >> 2][bj][(kk - 1) & 3][n], up = (kk == 7) ? dpp_next4(acc[0][bj][0][n]) : acc[(kk + 1) >> 2][bj][(kk + 1) & 3][n];
;                         const f32x4 c4 = um * w0 + acc[kk >> 2][bj][kk & 3][n] * w1 + up * w2 + bb;
;                         typedef unsigned u32x2_ __attribute__((ext_vector_type(2)));
;                         u32x2_ w; w.x = cvt_pk_bf16(c4[0] * epi_sigmoid(c4[0]), c4[1] * epi_sigmoid(c4[1])); w.y = cvt_pk_bf16(c4[2] * epi_sigmoid(c4[2]), c4[3] * epi_sigmoid(c4[3]));
;                         *(u32x2_*)(xbc + (size_t)(row0 + kk) * 10240 + ch) = w;
	v_pk_mul_f32 v[178:179], v[110:111], v[142:143]
	v_pk_fma_f32 v[180:181], v[124:125], v[136:137], v[180:181]
	v_pk_fma_f32 v[178:179], v[126:127], v[138:139], v[178:179]
	v_pk_fma_f32 v[180:181], v[100:101], v[116:117], v[180:181]
	v_pk_fma_f32 v[178:179], v[102:103], v[118:119], v[178:179]
	v_pk_add_f32 v[180:181], v[112:113], v[180:181]
	v_pk_add_f32 v[178:179], v[114:115], v[178:179]
	v_mul_f32_e32 v169, 0xbfb8aa3b, v180
	v_exp_f32_e32 v169, v169
	v_mul_f32_e32 v171, 0xbfb8aa3b, v181
	v_exp_f32_e32 v171, v171
	v_pk_fma_f32 v[208:209], v[84:85], v[136:137], v[208:209]
	v_add_f32_e32 v169, 1.0, v169
	v_rcp_f32_e32 v169, v169
	v_add_f32_e32 v171, 1.0, v171
	v_rcp_f32_e32 v171, v171
	v_pk_fma_f32 v[208:209], v[68:69], v[116:117], v[208:209]
	v_mul_f32_e32 v169, v180, v169
	v_pk_add_f32 v[208:209], v[112:113], v[208:209]
	v_mul_f32_e32 v171, v181, v171
	v_cvt_pk_bf16_f32 v180, v169, v171
	v_mul_f32_e32 v169, 0xbfb8aa3b, v178
	v_exp_f32_e32 v169, v169
	v_mul_f32_e32 v171, 0xbfb8aa3b, v179
	v_exp_f32_e32 v171, v171
	v_pk_mul_f32 v[140:141], v[68:69], v[140:141]
	v_add_f32_e32 v169, 1.0, v169
	v_rcp_f32_e32 v169, v169
	v_add_f32_e32 v171, 1.0, v171
	v_rcp_f32_e32 v171, v171
	v_pk_fma_f32 v[136:137], v[76:77], v[136:137], v[140:141]
	v_mul_f32_e32 v169, v178, v169
	v_mul_f32_e32 v171, v179, v171
	v_cvt_pk_bf16_f32 v181, v169, v171
	v_or_b32_e32 v169, 2, v172
	v_mad_i64_i32 v[178:179], s[4:5], v169, s93, v[188:189]
	v_mul_f32_e32 v169, 0xbfb8aa3b, v182
	v_exp_f32_e32 v169, v169
	v_mul_f32_e32 v171, 0xbfb8aa3b, v183
	v_exp_f32_e32 v171, v171
	v_lshl_add_u64 v[178:179], v[178:179], 0, v[194:195]
	v_add_f32_e32 v169, 1.0, v169
	v_rcp_f32_e32 v169, v169
	v_add_f32_e32 v171, 1.0, v171
	global_store_dwordx2 v[178:179], v[180:181], off
	v_pk_mul_f32 v[180:181], v[102:103], v[142:143]
	v_rcp_f32_e32 v171, v171
	v_pk_fma_f32 v[180:181], v[110:111], v[138:139], v[180:181]
	v_mul_f32_e32 v169, v182, v169
	v_pk_fma_f32 v[180:181], v[94:95], v[118:119], v[180:181]
	v_mul_f32_e32 v171, v183, v171
	v_pk_add_f32 v[180:181], v[114:115], v[180:181]
	v_cvt_pk_bf16_f32 v182, v169, v171
	s_nop 0
	v_mul_f32_e32 v169, 0xbfb8aa3b, v180
	v_exp_f32_e32 v169, v169
	v_mul_f32_e32 v171, 0xbfb8aa3b, v181
	v_exp_f32_e32 v171, v171
	v_add_f32_e32 v169, 1.0, v169
	v_rcp_f32_e32 v169, v169
	v_add_f32_e32 v171, 1.0, v171
	v_rcp_f32_e32 v171, v171
	v_mul_f32_e32 v169, v180, v169
	v_mul_f32_e32 v171, v181, v171
	v_cvt_pk_bf16_f32 v183, v169, v171
	v_or_b32_e32 v169, 3, v172
	v_mad_i64_i32 v[180:181], s[4:5], v169, s93, v[188:189]
	v_mul_f32_e32 v169, 0xbfb8aa3b, v184
	v_exp_f32_e32 v169, v169
	v_mul_f32_e32 v171, 0xbfb8aa3b, v185
	v_exp_f32_e32 v171, v171
	v_lshl_add_u64 v[180:181], v[180:181], 0, v[194:195]
	v_add_f32_e32 v169, 1.0, v169
	v_rcp_f32_e32 v169, v169
	v_add_f32_e32 v171, 1.0, v171
	global_store_dwordx2 v[180:181], v[182:183], off
	v_pk_mul_f32 v[182:183], v[94:95], v[142:143]
	v_rcp_f32_e32 v171, v171
	v_pk_fma_f32 v[182:183], v[102:103], v[138:139], v[182:183]
	v_mul_f32_e32 v169, v184, v169
	v_pk_fma_f32 v[182:183], v[86:87], v[118:119], v[182:183]
	v_mul_f32_e32 v171, v185, v171
	v_pk_add_f32 v[182:183], v[114:115], v[182:183]
	v_cvt_pk_bf16_f32 v184, v169, v171
	s_nop 0
	v_mul_f32_e32 v169, 0xbfb8aa3b, v182
	v_exp_f32_e32 v169, v169
	v_mul_f32_e32 v171, 0xbfb8aa3b, v183
	v_exp_f32_e32 v171, v171
	v_add_f32_e32 v169, 1.0, v169
	v_rcp_f32_e32 v169, v169
	v_add_f32_e32 v171, 1.0, v171
	v_rcp_f32_e32 v171, v171
	v_mul_f32_e32 v169, v182, v169
	v_mul_f32_e32 v171, v183, v171
	v_cvt_pk_bf16_f32 v185, v169, v171
	v_or_b32_e32 v169, 4, v172
	v_mad_i64_i32 v[182:183], s[4:5], v169, s93, v[188:189]
	v_mul_f32_e32 v169, 0xbfb8aa3b, v186
	v_exp_f32_e32 v169, v169
	v_mul_f32_e32 v171, 0xbfb8aa3b, v187
	v_exp_f32_e32 v171, v171
	v_lshl_add_u64 v[182:183], v[182:183], 0, v[194:195]
	v_add_f32_e32 v169, 1.0, v169
	v_rcp_f32_e32 v169, v169
	v_add_f32_e32 v171, 1.0, v171
	global_store_dwordx2 v[182:183], v[184:185], off
	v_pk_mul_f32 v[184:185], v[86:87], v[142:143]
	v_rcp_f32_e32 v171, v171
	v_pk_fma_f32 v[184:185], v[94:95], v[138:139], v[184:185]
	v_mul_f32_e32 v169, v186, v169
	v_pk_fma_f32 v[184:185], v[78:79], v[118:119], v[184:185]
; __device__ __forceinline__ unsigned cvt_pk_bf16(float lo, float hi) { unsigned r; asm volatile("v_cvt_pk_bf16_f32 %0, %1, %2" : "=v"(r) : "v"(lo), "v"(hi)); return r; }
; __device__ __forceinline__ float epi_sigmoid(float v) { return __builtin_amdgcn_rcpf(1.0f + __expf(-v)); }
; __device__ __forceinline__ f32x4 dpp_prev4(const f32x4& v) { return (f32x4){dpp_prev(v[0]), dpp_prev(v[1]), dpp_prev(v[2]), dpp_prev(v[3])}; }
; __device__ __forceinline__ f32x4 dpp_next4(const f32x4& v) { return (f32x4){dpp_next(v[0]), dpp_next(v[1]), dpp_next(v[2]), dpp_next(v[3])}; }
;     __device__ __forceinline__ void operator()(const f32x4 (&acc)[2][2][4][2], const Unit& u, int wr, int wc, int fr, int fq) const {
;     ...
;                     for (int kk = 0; kk < 8; ++kk) {
;                         const f32x4 um = (kk == 0) ? dpp_prev4(acc[1][bj][3][n]) : acc[(kk - 1) >> 2][bj][(kk - 1) & 3][n], up = (kk == 7) ? dpp_next4(acc[0][bj][0][n]) : acc[(kk + 1) >> 2][bj][(kk + 1) & 3][n];
;                         const f32x4 c4 = um * w0 + acc[kk >> 2][bj][kk & 3][n] * w1 + up * w2 + bb;
;                         typedef unsigned u32x2_ __attribute__((ext_vector_type(2)));
;                         u32x2_ w; w.x = cvt_pk_bf16(c4[0] * epi_sigmoid(c4[0]), c4[1] * epi_sigmoid(c4[1])); w.y = cvt_pk_bf16(c4[2] * epi_sigmoid(c4[2]), c4[3] * epi_sigmoid(c4[3]));
;                         *(u32x2_*)(xbc + (size_t)(row0 + kk) * 10240 + ch) = w;
;                     }
;                     if (fr == 0) { float* ep = edge + ((size_t)seg * 4 + 0) * 10240 + ch; *(f32x4*)ep = acc[0][bj][0][n]; *(f32x4*)(ep + 10240) = acc[0][bj][1][n]; }
;                     if (fr == 15) { float* ep = edge + ((size_t)seg * 4 + 2) * 10240 + ch; *(f32x4*)ep = acc[1][bj][2][n]; *(f32x4*)(ep + 10240) = acc[1][bj][3][n]; }
	v_mul_f32_e32 v171, v187, v171
	v_pk_add_f32 v[184:185], v[114:115], v[184:185]
	v_cvt_pk_bf16_f32 v186, v169, v171
	s_nop 0
	v_mul_f32_e32 v169, 0xbfb8aa3b, v184
	v_exp_f32_e32 v169, v169
	v_mul_f32_e32 v171, 0xbfb8aa3b, v185
	v_exp_f32_e32 v171, v171
	v_add_f32_e32 v169, 1.0, v169
	v_rcp_f32_e32 v169, v169
	v_add_f32_e32 v171, 1.0, v171
	v_rcp_f32_e32 v171, v171
	v_mul_f32_e32 v169, v184, v169
	v_mul_f32_e32 v171, v185, v171
	v_cvt_pk_bf16_f32 v187, v169, v171
	v_or_b32_e32 v169, 5, v172
	v_mad_i64_i32 v[184:185], s[4:5], v169, s93, v[188:189]
	v_mul_f32_e32 v169, 0xbfb8aa3b, v208
	v_exp_f32_e32 v169, v169
	v_mul_f32_e32 v171, 0xbfb8aa3b, v209
	v_exp_f32_e32 v171, v171
	v_lshl_add_u64 v[184:185], v[184:185], 0, v[194:195]
	v_add_f32_e32 v169, 1.0, v169
	v_rcp_f32_e32 v169, v169
	v_add_f32_e32 v171, 1.0, v171
	global_store_dwordx2 v[184:185], v[186:187], off
	v_pk_mul_f32 v[186:187], v[78:79], v[142:143]
	v_rcp_f32_e32 v171, v171
	v_pk_fma_f32 v[186:187], v[86:87], v[138:139], v[186:187]
	v_mul_f32_e32 v169, v208, v169
	v_pk_fma_f32 v[186:187], v[70:71], v[118:119], v[186:187]
	v_mul_f32_e32 v171, v209, v171
	v_pk_add_f32 v[186:187], v[114:115], v[186:187]
	v_cvt_pk_bf16_f32 v208, v169, v171
	v_pk_mul_f32 v[142:143], v[70:71], v[142:143]
	v_mul_f32_e32 v169, 0xbfb8aa3b, v186
	v_exp_f32_e32 v169, v169
	v_mul_f32_e32 v171, 0xbfb8aa3b, v187
	v_exp_f32_e32 v171, v171
	v_pk_fma_f32 v[138:139], v[78:79], v[138:139], v[142:143]
	v_add_f32_e32 v169, 1.0, v169
	v_rcp_f32_e32 v169, v169
	v_add_f32_e32 v171, 1.0, v171
	v_rcp_f32_e32 v171, v171
	v_pk_fma_f32 v[118:119], v[118:119], v[210:211], v[138:139]
	v_mul_f32_e32 v169, v186, v169
	v_pk_add_f32 v[114:115], v[114:115], v[118:119]
	v_mul_f32_e32 v171, v187, v171
	v_cvt_pk_bf16_f32 v209, v169, v171
	v_or_b32_e32 v169, 6, v172
	v_mad_i64_i32 v[186:187], s[4:5], v169, s93, v[188:189]
	v_lshl_add_u64 v[186:187], v[186:187], 0, v[194:195]
	global_store_dwordx2 v[186:187], v[208:209], off
	v_mov_b32_dpp v208, v132 row_shl:1 row_mask:0xf bank_mask:0xf bound_ctrl:1
	v_mov_b32_dpp v209, v133 row_shl:1 row_mask:0xf bank_mask:0xf bound_ctrl:1
	v_pk_fma_f32 v[116:117], v[116:117], v[208:209], v[136:137]
	s_nop 0
	v_pk_add_f32 v[112:113], v[112:113], v[116:117]
	s_nop 0
	v_mul_f32_e32 v116, 0xbfb8aa3b, v112
	v_exp_f32_e32 v116, v116
	s_nop 0
	v_add_f32_e32 v116, 1.0, v116
	v_rcp_f32_e32 v116, v116
	s_nop 0
	v_mul_f32_e32 v112, v112, v116
	v_mul_f32_e32 v116, 0xbfb8aa3b, v113
	v_exp_f32_e32 v116, v116
	s_nop 0
	v_add_f32_e32 v116, 1.0, v116
	v_rcp_f32_e32 v116, v116
	s_nop 0
	v_mul_f32_e32 v113, v113, v116
	v_cvt_pk_bf16_f32 v112, v112, v113
	v_mul_f32_e32 v113, 0xbfb8aa3b, v114
	v_exp_f32_e32 v113, v113
	s_nop 0
	v_add_f32_e32 v113, 1.0, v113
	v_rcp_f32_e32 v113, v113
	s_nop 0
	v_mul_f32_e32 v113, v114, v113
	v_mul_f32_e32 v114, 0xbfb8aa3b, v115
	v_exp_f32_e32 v114, v114
	s_nop 0
	v_add_f32_e32 v114, 1.0, v114
	v_rcp_f32_e32 v114, v114
	s_nop 0
	v_mul_f32_e32 v114, v115, v114
	v_cvt_pk_bf16_f32 v113, v113, v114
	v_or_b32_e32 v114, 7, v172
	v_mad_i64_i32 v[114:115], s[4:5], v114, s93, v[188:189]
	v_lshl_add_u64 v[188:189], v[114:115], 0, v[194:195]
	global_store_dwordx2 v[188:189], v[112:113], off
	s_and_saveexec_b64 s[4:5], vcc
	s_xor_b64 s[4:5], exec, s[4:5]
	s_add_u32 s0, s77, s31
	s_addc_u32 s1, s78, s19
	s_add_u32 s40, s0, 0x14000
	s_addc_u32 s41, s1, 0
	s_mov_b64 s[0:1], exec
	s_or_saveexec_b64 s[4:5], s[4:5]
	v_mov_b64_e32 v[114:115], v[70:71]
	v_mov_b64_e32 v[118:119], v[78:79]
	v_mov_b64_e32 v[136:137], s[40:41]
	v_mov_b64_e32 v[112:113], v[68:69]
	v_mov_b64_e32 v[116:117], v[76:77]
	s_xor_b64 exec, exec, s[4:5]
	s_cbranch_execz .LBB0_197
	v_cmp_eq_u32_e32 vcc, 0, v196
	s_mov_b64 s[42:43], s[0:1]
	s_and_saveexec_b64 s[44:45], vcc
	s_add_u32 s40, s77, s31
	s_addc_u32 s41, s78, s19
	s_or_b64 s[42:43], s[0:1], exec
	s_or_b64 exec, exec, s[44:45]
	v_mov_b64_e32 v[136:137], s[40:41]
	s_andn2_b64 s[0:1], s[0:1], exec
	s_and_b64 s[40:41], s[42:43], exec
	v_mov_b64_e32 v[112:113], v[124:125]
	v_mov_b64_e32 v[116:117], v[132:133]
	s_or_b64 s[0:1], s[0:1], s[40:41]
	v_mov_b64_e32 v[114:115], v[126:127]
	v_mov_b64_e32 v[118:119], v[134:135]

; __device__ __forceinline__ unsigned cvt_pk_bf16(float lo, float hi) { unsigned r; asm volatile("v_cvt_pk_bf16_f32 %0, %1, %2" : "=v"(r) : "v"(lo), "v"(hi)); return r; }
; __device__ __forceinline__ float epi_sigmoid(float v) { return __builtin_amdgcn_rcpf(1.0f + __expf(-v)); }
; __device__ __forceinline__ f32x4 dpp_prev4(const f32x4& v) { return (f32x4){dpp_prev(v[0]), dpp_prev(v[1]), dpp_prev(v[2]), dpp_prev(v[3])}; }
; __device__ __forceinline__ f32x4 dpp_next4(const f32x4& v) { return (f32x4){dpp_next(v[0]), dpp_next(v[1]), dpp_next(v[2]), dpp_next(v[3])}; }
;     __device__ __forceinline__ void operator()(const f32x4 (&acc)[2][2][4][2], const Unit& u, int wr, int wc, int fr, int fq) const {
;     ...
;             for (int bj = 0; bj < 2; ++bj)
; #pragma unroll
;                 for (int n = 0; n < 2; ++n) {
;                     const int ch = (pn - 32) * 256 + bj * HALF + cw_ + 4 * n;
;                     const f32x4 w0 = *(const f32x4*)(cw + ch), w1 = *(const f32x4*)(cw + 10240 + ch), w2 = *(const f32x4*)(cw + 2 * 10240 + ch), bb = *(const f32x4*)(cb + ch);
; #pragma unroll
;                     for (int kk = 0; kk < 8; ++kk) {
;                         const f32x4 um = (kk == 0) ? dpp_prev4(acc[1][bj][3][n]) : acc[(kk - 1) >> 2][bj][(kk - 1) & 3][n], up = (kk == 7) ? dpp_next4(acc[0][bj][0][n]) : acc[(kk + 1) >> 2][bj][(kk + 1) & 3][n];
;                         const f32x4 c4 = um * w0 + acc[kk >> 2][bj][kk & 3][n] * w1 + up * w2 + bb;
;                         typedef unsigned u32x2_ __attribute__((ext_vector_type(2)));
;                         u32x2_ w; w.x = cvt_pk_bf16(c4[0] * epi_sigmoid(c4[0]), c4[1] * epi_sigmoid(c4[1])); w.y = cvt_pk_bf16(c4[2] * epi_sigmoid(c4[2]), c4[3] * epi_sigmoid(c4[3]));
;                         *(u32x2_*)(xbc + (size_t)(row0 + kk) * 10240 + ch) = w;
.LBB0_199:
	s_or_b64 exec, exec, s[4:5]
	s_nop 0
	v_or_b32_e32 v112, 4, v152
	v_mov_b32_e32 v113, v153
	v_lshlrev_b64 v[112:113], 2, v[112:113]
	v_lshl_add_u64 v[114:115], s[26:27], 0, v[112:113]
	v_lshl_add_u64 v[112:113], s[28:29], 0, v[112:113]
	s_nop 0
	v_mov_b32_e32 v136, v212
	v_mov_b32_e32 v137, v213
	v_mov_b32_e32 v138, v214
	v_mov_b32_e32 v139, v215
	v_mov_b32_e32 v140, v216
	v_mov_b32_e32 v141, v217
	v_mov_b32_e32 v142, v218
	v_mov_b32_e32 v143, v219
	v_mov_b32_e32 v116, v220
	v_mov_b32_e32 v117, v221
	v_mov_b32_e32 v118, v222
	v_mov_b32_e32 v119, v223
	v_mov_b32_e32 v112, v224
	v_mov_b32_e32 v113, v225
	v_mov_b32_e32 v114, v226
	v_mov_b32_e32 v115, v227
	global_load_dwordx4 v[212:215], v[174:175], off offset:528
	global_load_dwordx4 v[216:219], v[244:245], off offset:528
	global_load_dwordx4 v[220:223], v[246:247], off offset:528
	global_load_dwordx4 v[224:227], v[176:177], off offset:528
	v_mov_b32_dpp v194, v64 row_shr:1 row_mask:0xf bank_mask:0xf bound_ctrl:1
	v_mov_b32_dpp v195, v65 row_shr:1 row_mask:0xf bank_mask:0xf bound_ctrl:1
	v_mov_b32_dpp v208, v66 row_shr:1 row_mask:0xf bank_mask:0xf bound_ctrl:1
	v_mov_b32_dpp v209, v67 row_shr:1 row_mask:0xf bank_mask:0xf bound_ctrl:1
	v_cmp_lt_i32_e32 vcc, 14, v196
	s_mov_b64 s[0:1], 0
	v_pk_mul_f32 v[194:195], v[136:137], v[194:195]
	v_pk_mul_f32 v[208:209], v[138:139], v[208:209]
	v_pk_fma_f32 v[194:195], v[128:129], v[140:141], v[194:195]
	v_pk_fma_f32 v[208:209], v[130:131], v[142:143], v[208:209]
	v_pk_fma_f32 v[194:195], v[120:121], v[116:117], v[194:195]
	v_pk_fma_f32 v[208:209], v[122:123], v[118:119], v[208:209]
	v_pk_add_f32 v[194:195], v[112:113], v[194:195]
	v_pk_add_f32 v[208:209], v[114:115], v[208:209]
	v_mul_f32_e32 v169, 0xbfb8aa3b, v194
	v_mul_f32_e32 v171, 0xbfb8aa3b, v195
	v_exp_f32_e32 v169, v169
	v_exp_f32_e32 v171, v171
	v_add_f32_e32 v169, 1.0, v169
	v_add_f32_e32 v171, 1.0, v171
	v_rcp_f32_e32 v169, v169
	v_rcp_f32_e32 v171, v171
	v_mul_f32_e32 v169, v194, v169
	v_mul_f32_e32 v171, v195, v171
	v_cvt_pk_bf16_f32 v194, v169, v171
	v_mul_f32_e32 v169, 0xbfb8aa3b, v208
	v_mul_f32_e32 v171, 0xbfb8aa3b, v209
	v_exp_f32_e32 v169, v169
	v_exp_f32_e32 v171, v171
	v_add_f32_e32 v169, 1.0, v169
	v_add_f32_e32 v171, 1.0, v171
	v_rcp_f32_e32 v169, v169
	v_rcp_f32_e32 v171, v171
	v_mul_f32_e32 v169, v208, v169
	v_mul_f32_e32 v171, v209, v171
	v_pk_mul_f32 v[208:209], v[120:121], v[140:141]
	v_cvt_pk_bf16_f32 v195, v169, v171
	global_store_dwordx2 v[190:191], v[194:195], off offset:8
	v_pk_fma_f32 v[208:209], v[128:129], v[136:137], v[208:209]
	v_pk_mul_f32 v[194:195], v[122:123], v[142:143]
	v_pk_fma_f32 v[208:209], v[104:105], v[116:117], v[208:209]
	v_pk_fma_f32 v[194:195], v[130:131], v[138:139], v[194:195]
	v_pk_add_f32 v[208:209], v[112:113], v[208:209]
	v_pk_fma_f32 v[194:195], v[106:107], v[118:119], v[194:195]
	v_mul_f32_e32 v169, 0xbfb8aa3b, v208
	v_mul_f32_e32 v171, 0xbfb8aa3b, v209
	v_exp_f32_e32 v169, v169
	v_exp_f32_e32 v171, v171
	v_pk_add_f32 v[194:195], v[114:115], v[194:195]
	v_add_f32_e32 v169, 1.0, v169
	v_add_f32_e32 v171, 1.0, v171
	v_rcp_f32_e32 v169, v169
	v_rcp_f32_e32 v171, v171
	v_mul_f32_e32 v169, v208, v169
	v_mul_f32_e32 v171, v209, v171
	v_cvt_pk_bf16_f32 v208, v169, v171
	v_mul_f32_e32 v169, 0xbfb8aa3b, v194
	v_mul_f32_e32 v171, 0xbfb8aa3b, v195
	v_exp_f32_e32 v169, v169
	v_exp_f32_e32 v171, v171
	v_add_f32_e32 v169, 1.0, v169
	v_add_f32_e32 v171, 1.0, v171
	v_rcp_f32_e32 v169, v169
	v_rcp_f32_e32 v171, v171
	v_mul_f32_e32 v169, v194, v169
	v_mul_f32_e32 v171, v195, v171
	v_cvt_pk_bf16_f32 v209, v169, v171
	global_store_dwordx2 v[192:193], v[208:209], off offset:8
	v_pk_mul_f32 v[208:209], v[104:105], v[140:141]
	v_pk_mul_f32 v[194:195], v[106:107], v[142:143]
	v_pk_fma_f32 v[208:209], v[120:121], v[136:137], v[208:209]
	v_pk_fma_f32 v[194:195], v[122:123], v[138:139], v[194:195]
	v_pk_fma_f32 v[208:209], v[96:97], v[116:117], v[208:209]
	v_pk_fma_f32 v[194:195], v[98:99], v[118:119], v[194:195]
	v_pk_add_f32 v[208:209], v[112:113], v[208:209]
	v_pk_add_f32 v[194:195], v[114:115], v[194:195]
	v_mul_f32_e32 v169, 0xbfb8aa3b, v208
	v_mul_f32_e32 v171, 0xbfb8aa3b, v209
	v_exp_f32_e32 v169, v169
	v_exp_f32_e32 v171, v171
	v_add_f32_e32 v169, 1.0, v169
	v_add_f32_e32 v171, 1.0, v171
	v_rcp_f32_e32 v169, v169
	v_rcp_f32_e32 v171, v171
	v_mul_f32_e32 v169, v208, v169
	v_mul_f32_e32 v171, v209, v171
	v_cvt_pk_bf16_f32 v208, v169, v171
	v_mul_f32_e32 v169, 0xbfb8aa3b, v194
	v_mul_f32_e32 v171, 0xbfb8aa3b, v195
	v_exp_f32_e32 v169, v169
	v_exp_f32_e32 v171, v171
	v_add_f32_e32 v169, 1.0, v169
	v_add_f32_e32 v171, 1.0, v171
	v_rcp_f32_e32 v169, v169
	v_rcp_f32_e32 v171, v171
	v_mul_f32_e32 v169, v194, v169
	v_mul_f32_e32 v171, v195, v171
	v_cvt_pk_bf16_f32 v209, v169, v171
	global_store_dwordx2 v[178:179], v[208:209], off offset:8
	v_pk_mul_f32 v[208:209], v[96:97], v[140:141]
	v_pk_mul_f32 v[194:195], v[98:99], v[142:143]
	v_pk_fma_f32 v[208:209], v[104:105], v[136:137], v[208:209]
	v_pk_fma_f32 v[194:195], v[106:107], v[138:139], v[194:195]
	v_pk_fma_f32 v[208:209], v[88:89], v[116:117], v[208:209]
	v_pk_fma_f32 v[194:195], v[90:91], v[118:119], v[194:195]
	v_pk_add_f32 v[208:209], v[112:113], v[208:209]
	v_pk_add_f32 v[194:195], v[114:115], v[194:195]
	v_mul_f32_e32 v169, 0xbfb8aa3b, v208
	v_mul_f32_e32 v171, 0xbfb8aa3b, v209
	v_exp_f32_e32 v169, v169
	v_exp_f32_e32 v171, v171
	v_add_f32_e32 v169, 1.0, v169
	v_add_f32_e32 v171, 1.0, v171
	v_rcp_f32_e32 v169, v169
	v_rcp_f32_e32 v171, v171
	v_mul_f32_e32 v169, v208, v169
	v_mul_f32_e32 v171, v209, v171
	v_cvt_pk_bf16_f32 v208, v169, v171
	v_mul_f32_e32 v169, 0xbfb8aa3b, v194
; __device__ __forceinline__ unsigned cvt_pk_bf16(float lo, float hi) { unsigned r; asm volatile("v_cvt_pk_bf16_f32 %0, %1, %2" : "=v"(r) : "v"(lo), "v"(hi)); return r; }
; __device__ __forceinline__ float epi_sigmoid(float v) { return __builtin_amdgcn_rcpf(1.0f + __expf(-v)); }
; __device__ __forceinline__ f32x4 dpp_prev4(const f32x4& v) { return (f32x4){dpp_prev(v[0]), dpp_prev(v[1]), dpp_prev(v[2]), dpp_prev(v[3])}; }
; __device__ __forceinline__ f32x4 dpp_next4(const f32x4& v) { return (f32x4){dpp_next(v[0]), dpp_next(v[1]), dpp_next(v[2]), dpp_next(v[3])}; }
;     __device__ __forceinline__ void operator()(const f32x4 (&acc)[2][2][4][2], const Unit& u, int wr, int wc, int fr, int fq) const {
;     ...
;                     for (int kk = 0; kk < 8; ++kk) {
;                         const f32x4 um = (kk == 0) ? dpp_prev4(acc[1][bj][3][n]) : acc[(kk - 1) >> 2][bj][(kk - 1) & 3][n], up = (kk == 7) ? dpp_next4(acc[0][bj][0][n]) : acc[(kk + 1) >> 2][bj][(kk + 1) & 3][n];
;                         const f32x4 c4 = um * w0 + acc[kk >> 2][bj][kk & 3][n] * w1 + up * w2 + bb;
;                         typedef unsigned u32x2_ __attribute__((ext_vector_type(2)));
;                         u32x2_ w; w.x = cvt_pk_bf16(c4[0] * epi_sigmoid(c4[0]), c4[1] * epi_sigmoid(c4[1])); w.y = cvt_pk_bf16(c4[2] * epi_sigmoid(c4[2]), c4[3] * epi_sigmoid(c4[3]));
;                         *(u32x2_*)(xbc + (size_t)(row0 + kk) * 10240 + ch) = w;
	v_mul_f32_e32 v171, 0xbfb8aa3b, v195
	v_exp_f32_e32 v169, v169
	v_exp_f32_e32 v171, v171
	v_add_f32_e32 v169, 1.0, v169
	v_add_f32_e32 v171, 1.0, v171
	v_rcp_f32_e32 v169, v169
	v_rcp_f32_e32 v171, v171
	v_mul_f32_e32 v169, v194, v169
	v_mul_f32_e32 v171, v195, v171
	v_cvt_pk_bf16_f32 v209, v169, v171
	global_store_dwordx2 v[180:181], v[208:209], off offset:8
	v_pk_mul_f32 v[208:209], v[88:89], v[140:141]
	v_pk_mul_f32 v[194:195], v[90:91], v[142:143]
	v_pk_fma_f32 v[208:209], v[96:97], v[136:137], v[208:209]
	v_pk_fma_f32 v[194:195], v[98:99], v[138:139], v[194:195]
	v_pk_fma_f32 v[208:209], v[80:81], v[116:117], v[208:209]
	v_pk_fma_f32 v[194:195], v[82:83], v[118:119], v[194:195]
	v_pk_add_f32 v[208:209], v[112:113], v[208:209]
	v_pk_add_f32 v[194:195], v[114:115], v[194:195]
	v_mul_f32_e32 v169, 0xbfb8aa3b, v208
	v_mul_f32_e32 v171, 0xbfb8aa3b, v209
	v_exp_f32_e32 v169, v169
	v_exp_f32_e32 v171, v171
	v_add_f32_e32 v169, 1.0, v169
	v_add_f32_e32 v171, 1.0, v171
	v_rcp_f32_e32 v169, v169
	v_rcp_f32_e32 v171, v171
	v_mul_f32_e32 v169, v208, v169
	v_mul_f32_e32 v171, v209, v171
	v_cvt_pk_bf16_f32 v208, v169, v171
	v_mul_f32_e32 v169, 0xbfb8aa3b, v194
	v_mul_f32_e32 v171, 0xbfb8aa3b, v195
	v_exp_f32_e32 v169, v169
	v_exp_f32_e32 v171, v171
	v_add_f32_e32 v169, 1.0, v169
	v_add_f32_e32 v171, 1.0, v171
	v_rcp_f32_e32 v169, v169
	v_rcp_f32_e32 v171, v171
	v_mul_f32_e32 v169, v194, v169
	v_mul_f32_e32 v171, v195, v171
	v_cvt_pk_bf16_f32 v209, v169, v171
	global_store_dwordx2 v[182:183], v[208:209], off offset:8
	v_pk_mul_f32 v[208:209], v[80:81], v[140:141]
	v_pk_mul_f32 v[194:195], v[82:83], v[142:143]
	v_pk_fma_f32 v[208:209], v[88:89], v[136:137], v[208:209]
	v_pk_fma_f32 v[194:195], v[90:91], v[138:139], v[194:195]
	v_pk_fma_f32 v[208:209], v[72:73], v[116:117], v[208:209]
	v_pk_fma_f32 v[194:195], v[74:75], v[118:119], v[194:195]
	v_pk_add_f32 v[208:209], v[112:113], v[208:209]
	v_pk_add_f32 v[194:195], v[114:115], v[194:195]
	v_mul_f32_e32 v169, 0xbfb8aa3b, v208
	v_mul_f32_e32 v171, 0xbfb8aa3b, v209
	v_exp_f32_e32 v169, v169
	v_exp_f32_e32 v171, v171
	v_add_f32_e32 v169, 1.0, v169
	v_add_f32_e32 v171, 1.0, v171
	v_rcp_f32_e32 v169, v169
	v_rcp_f32_e32 v171, v171
	v_mul_f32_e32 v169, v208, v169
	v_mul_f32_e32 v171, v209, v171
	v_cvt_pk_bf16_f32 v208, v169, v171
	v_mul_f32_e32 v169, 0xbfb8aa3b, v194
	v_mul_f32_e32 v171, 0xbfb8aa3b, v195
	v_exp_f32_e32 v169, v169
	v_exp_f32_e32 v171, v171
	v_add_f32_e32 v169, 1.0, v169
	v_add_f32_e32 v171, 1.0, v171
	v_rcp_f32_e32 v169, v169
	v_rcp_f32_e32 v171, v171
	v_mul_f32_e32 v169, v194, v169
	v_mul_f32_e32 v171, v195, v171
	v_cvt_pk_bf16_f32 v209, v169, v171
	global_store_dwordx2 v[184:185], v[208:209], off offset:8
	v_pk_mul_f32 v[208:209], v[72:73], v[140:141]
	v_pk_mul_f32 v[194:195], v[74:75], v[142:143]
	v_pk_fma_f32 v[208:209], v[80:81], v[136:137], v[208:209]
	v_pk_fma_f32 v[194:195], v[82:83], v[138:139], v[194:195]
	v_pk_fma_f32 v[208:209], v[64:65], v[116:117], v[208:209]
	v_pk_fma_f32 v[194:195], v[66:67], v[118:119], v[194:195]
	v_pk_add_f32 v[208:209], v[112:113], v[208:209]
	v_pk_add_f32 v[194:195], v[114:115], v[194:195]
	v_mul_f32_e32 v169, 0xbfb8aa3b, v208
	v_mul_f32_e32 v171, 0xbfb8aa3b, v209
	v_exp_f32_e32 v169, v169
	v_exp_f32_e32 v171, v171
	v_pk_mul_f32 v[140:141], v[64:65], v[140:141]
	v_pk_mul_f32 v[142:143], v[66:67], v[142:143]
	v_add_f32_e32 v169, 1.0, v169
	v_add_f32_e32 v171, 1.0, v171
	v_rcp_f32_e32 v169, v169
	v_rcp_f32_e32 v171, v171
	v_pk_fma_f32 v[136:137], v[72:73], v[136:137], v[140:141]
	v_pk_fma_f32 v[138:139], v[74:75], v[138:139], v[142:143]
	v_mul_f32_e32 v169, v208, v169
	v_mul_f32_e32 v171, v209, v171
	v_cvt_pk_bf16_f32 v208, v169, v171
	v_mul_f32_e32 v169, 0xbfb8aa3b, v194
	v_mul_f32_e32 v171, 0xbfb8aa3b, v195
	v_exp_f32_e32 v169, v169
	v_exp_f32_e32 v171, v171
	v_add_f32_e32 v169, 1.0, v169
	v_add_f32_e32 v171, 1.0, v171
	v_rcp_f32_e32 v169, v169
	v_rcp_f32_e32 v171, v171
	v_mul_f32_e32 v169, v194, v169
	v_mul_f32_e32 v171, v195, v171
	v_mov_b32_dpp v194, v128 row_shl:1 row_mask:0xf bank_mask:0xf bound_ctrl:1
	v_mov_b32_dpp v195, v129 row_shl:1 row_mask:0xf bank_mask:0xf bound_ctrl:1
	v_pk_fma_f32 v[116:117], v[116:117], v[194:195], v[136:137]
	v_cvt_pk_bf16_f32 v209, v169, v171
	global_store_dwordx2 v[186:187], v[208:209], off offset:8
	v_pk_add_f32 v[112:113], v[112:113], v[116:117]
	v_mov_b32_dpp v208, v130 row_shl:1 row_mask:0xf bank_mask:0xf bound_ctrl:1
	v_mul_f32_e32 v116, 0xbfb8aa3b, v112
	v_exp_f32_e32 v116, v116
	v_mov_b32_dpp v209, v131 row_shl:1 row_mask:0xf bank_mask:0xf bound_ctrl:1
	v_pk_fma_f32 v[118:119], v[118:119], v[208:209], v[138:139]
	v_add_f32_e32 v116, 1.0, v116
	v_rcp_f32_e32 v116, v116
	v_pk_add_f32 v[114:115], v[114:115], v[118:119]
	v_mul_f32_e32 v112, v112, v116
	v_mul_f32_e32 v116, 0xbfb8aa3b, v113
	v_exp_f32_e32 v116, v116
	s_nop 0
	v_add_f32_e32 v116, 1.0, v116
	v_rcp_f32_e32 v116, v116
	s_nop 0
	v_mul_f32_e32 v113, v113, v116
	v_cvt_pk_bf16_f32 v112, v112, v113
	v_mul_f32_e32 v113, 0xbfb8aa3b, v114
	v_exp_f32_e32 v113, v113
	s_nop 0
	v_add_f32_e32 v113, 1.0, v113
	v_rcp_f32_e32 v113, v113
	s_nop 0
	v_mul_f32_e32 v113, v114, v113
	v_mul_f32_e32 v114, 0xbfb8aa3b, v115
	v_exp_f32_e32 v114, v114
	s_nop 0
	v_add_f32_e32 v114, 1.0, v114
	v_rcp_f32_e32 v114, v114
	s_nop 0
	v_mul_f32_e32 v114, v115, v114
	v_cvt_pk_bf16_f32 v113, v113, v114
	global_store_dwordx2 v[188:189], v[112:113], off offset:8
	s_and_saveexec_b64 s[4:5], vcc
	s_xor_b64 s[4:5], exec, s[4:5]
	s_add_u32 s0, s77, s31
	s_addc_u32 s1, s78, s19
	s_add_u32 s40, s0, 0x14000
	s_addc_u32 s41, s1, 0
	s_mov_b64 s[0:1], exec
	s_or_saveexec_b64 s[4:5], s[4:5]
	v_mov_b64_e32 v[114:115], v[66:67]
	v_mov_b64_e32 v[118:119], v[74:75]
	v_mov_b64_e32 v[136:137], s[40:41]
	v_mov_b64_e32 v[112:113], v[64:65]
	v_mov_b64_e32 v[116:117], v[72:73]
	s_xor_b64 exec, exec, s[4:5]
	s_cbranch_execz .LBB0_205
	v_cmp_eq_u32_e32 vcc, 0, v196
	s_mov_b64 s[42:43], s[0:1]
	s_and_saveexec_b64 s[44:45], vcc
	s_add_u32 s40, s77, s31
	s_addc_u32 s41, s78, s19
	s_or_b64 s[42:43], s[0:1], exec
	s_or_b64 exec, exec, s[44:45]
	v_mov_b64_e32 v[136:137], s[40:41]
	s_andn2_b64 s[0:1], s[0:1], exec
	s_and_b64 s[40:41], s[42:43], exec
	v_mov_b64_e32 v[112:113], v[120:121]
	v_mov_b64_e32 v[116:117], v[128:129]
	s_or_b64 s[0:1], s[0:1], s[40:41]
	v_mov_b64_e32 v[114:115], v[122:123]
	v_mov_b64_e32 v[118:119], v[130:131]

; __device__ __forceinline__ unsigned cvt_pk_bf16(float lo, float hi) { unsigned r; asm volatile("v_cvt_pk_bf16_f32 %0, %1, %2" : "=v"(r) : "v"(lo), "v"(hi)); return r; }
; __device__ __forceinline__ float epi_sigmoid(float v) { return __builtin_amdgcn_rcpf(1.0f + __expf(-v)); }
; __device__ __forceinline__ f32x4 dpp_prev4(const f32x4& v) { return (f32x4){dpp_prev(v[0]), dpp_prev(v[1]), dpp_prev(v[2]), dpp_prev(v[3])}; }
; __device__ __forceinline__ f32x4 dpp_next4(const f32x4& v) { return (f32x4){dpp_next(v[0]), dpp_next(v[1]), dpp_next(v[2]), dpp_next(v[3])}; }
;     __device__ __forceinline__ void operator()(const f32x4 (&acc)[2][2][4][2], const Unit& u, int wr, int wc, int fr, int fq) const {
;     ...
;             for (int bj = 0; bj < 2; ++bj)
; #pragma unroll
;                 for (int n = 0; n < 2; ++n) {
;                     const int ch = (pn - 32) * 256 + bj * HALF + cw_ + 4 * n;
;                     const f32x4 w0 = *(const f32x4*)(cw + ch), w1 = *(const f32x4*)(cw + 10240 + ch), w2 = *(const f32x4*)(cw + 2 * 10240 + ch), bb = *(const f32x4*)(cb + ch);
; #pragma unroll
;                     for (int kk = 0; kk < 8; ++kk) {
;                         const f32x4 um = (kk == 0) ? dpp_prev4(acc[1][bj][3][n]) : acc[(kk - 1) >> 2][bj][(kk - 1) & 3][n], up = (kk == 7) ? dpp_next4(acc[0][bj][0][n]) : acc[(kk + 1) >> 2][bj][(kk + 1) & 3][n];
;                         const f32x4 c4 = um * w0 + acc[kk >> 2][bj][kk & 3][n] * w1 + up * w2 + bb;
;                         typedef unsigned u32x2_ __attribute__((ext_vector_type(2)));
;                         u32x2_ w; w.x = cvt_pk_bf16(c4[0] * epi_sigmoid(c4[0]), c4[1] * epi_sigmoid(c4[1])); w.y = cvt_pk_bf16(c4[2] * epi_sigmoid(c4[2]), c4[3] * epi_sigmoid(c4[3]));
;                         *(u32x2_*)(xbc + (size_t)(row0 + kk) * 10240 + ch) = w;
.LBB0_207:
	s_or_b64 exec, exec, s[4:5]
	s_nop 0
	v_or_b32_e32 v112, 0x80, v152
	v_mov_b32_e32 v113, v153
	v_lshlrev_b64 v[112:113], 2, v[112:113]
	v_lshl_add_u64 v[114:115], s[26:27], 0, v[112:113]
	v_lshl_add_u64 v[112:113], s[28:29], 0, v[112:113]
	s_nop 0
	v_mov_b32_e32 v136, v228
	v_mov_b32_e32 v137, v229
	v_mov_b32_e32 v138, v230
	v_mov_b32_e32 v139, v231
	v_mov_b32_e32 v140, v232
	v_mov_b32_e32 v141, v233
	v_mov_b32_e32 v142, v234
	v_mov_b32_e32 v143, v235
	v_mov_b32_e32 v116, v236
	v_mov_b32_e32 v117, v237
	v_mov_b32_e32 v118, v238
	v_mov_b32_e32 v119, v239
	v_mov_b32_e32 v112, v240
	v_mov_b32_e32 v113, v241
	v_mov_b32_e32 v114, v242
	v_mov_b32_e32 v115, v243
	v_mov_b32_dpp v194, v4 row_shr:1 row_mask:0xf bank_mask:0xf bound_ctrl:1
	v_mov_b32_dpp v195, v5 row_shr:1 row_mask:0xf bank_mask:0xf bound_ctrl:1
	v_mov_b32_dpp v208, v6 row_shr:1 row_mask:0xf bank_mask:0xf bound_ctrl:1
	v_mov_b32_dpp v209, v7 row_shr:1 row_mask:0xf bank_mask:0xf bound_ctrl:1
	v_cmp_lt_i32_e32 vcc, 14, v196
	s_mov_b64 s[0:1], 0
	v_pk_mul_f32 v[194:195], v[136:137], v[194:195]
	v_pk_mul_f32 v[208:209], v[138:139], v[208:209]
	v_pk_fma_f32 v[194:195], v[60:61], v[140:141], v[194:195]
	v_pk_fma_f32 v[208:209], v[62:63], v[142:143], v[208:209]
	v_pk_fma_f32 v[194:195], v[52:53], v[116:117], v[194:195]
	v_pk_fma_f32 v[208:209], v[54:55], v[118:119], v[208:209]
	v_pk_add_f32 v[194:195], v[112:113], v[194:195]
	v_pk_add_f32 v[208:209], v[114:115], v[208:209]
	v_mul_f32_e32 v169, 0xbfb8aa3b, v194
	v_mul_f32_e32 v171, 0xbfb8aa3b, v195
	v_exp_f32_e32 v169, v169
	v_exp_f32_e32 v171, v171
	v_add_f32_e32 v169, 1.0, v169
	v_add_f32_e32 v171, 1.0, v171
	v_rcp_f32_e32 v169, v169
	v_rcp_f32_e32 v171, v171
	v_mul_f32_e32 v169, v194, v169
	v_mul_f32_e32 v171, v195, v171
	v_cvt_pk_bf16_f32 v194, v169, v171
	v_mul_f32_e32 v169, 0xbfb8aa3b, v208
	v_mul_f32_e32 v171, 0xbfb8aa3b, v209
	v_exp_f32_e32 v169, v169
	v_exp_f32_e32 v171, v171
	v_add_f32_e32 v169, 1.0, v169
	v_add_f32_e32 v171, 1.0, v171
	v_rcp_f32_e32 v169, v169
	v_rcp_f32_e32 v171, v171
	v_mul_f32_e32 v169, v208, v169
	v_mul_f32_e32 v171, v209, v171
	v_pk_mul_f32 v[208:209], v[52:53], v[140:141]
	v_cvt_pk_bf16_f32 v195, v169, v171
	global_store_dwordx2 v[190:191], v[194:195], off offset:256
	v_pk_fma_f32 v[208:209], v[60:61], v[136:137], v[208:209]
	v_pk_mul_f32 v[194:195], v[54:55], v[142:143]
	v_pk_fma_f32 v[208:209], v[44:45], v[116:117], v[208:209]
	v_pk_fma_f32 v[194:195], v[62:63], v[138:139], v[194:195]
	v_pk_add_f32 v[208:209], v[112:113], v[208:209]
	v_pk_fma_f32 v[194:195], v[46:47], v[118:119], v[194:195]
	v_mul_f32_e32 v169, 0xbfb8aa3b, v208
	v_mul_f32_e32 v171, 0xbfb8aa3b, v209
	v_exp_f32_e32 v169, v169
	v_exp_f32_e32 v171, v171
	v_pk_add_f32 v[194:195], v[114:115], v[194:195]
	v_add_f32_e32 v169, 1.0, v169
	v_add_f32_e32 v171, 1.0, v171
	v_rcp_f32_e32 v169, v169
	v_rcp_f32_e32 v171, v171
	v_mul_f32_e32 v169, v208, v169
	v_mul_f32_e32 v171, v209, v171
	v_cvt_pk_bf16_f32 v208, v169, v171
	v_mul_f32_e32 v169, 0xbfb8aa3b, v194
	v_mul_f32_e32 v171, 0xbfb8aa3b, v195
	v_exp_f32_e32 v169, v169
	v_exp_f32_e32 v171, v171
	v_add_f32_e32 v169, 1.0, v169
	v_add_f32_e32 v171, 1.0, v171
	v_rcp_f32_e32 v169, v169
	v_rcp_f32_e32 v171, v171
	v_mul_f32_e32 v169, v194, v169
	v_mul_f32_e32 v171, v195, v171
	v_cvt_pk_bf16_f32 v209, v169, v171
	global_store_dwordx2 v[192:193], v[208:209], off offset:256
	v_pk_mul_f32 v[208:209], v[44:45], v[140:141]
	v_pk_mul_f32 v[194:195], v[46:47], v[142:143]
	v_pk_fma_f32 v[208:209], v[52:53], v[136:137], v[208:209]
	v_pk_fma_f32 v[194:195], v[54:55], v[138:139], v[194:195]
	v_pk_fma_f32 v[208:209], v[36:37], v[116:117], v[208:209]
	v_pk_fma_f32 v[194:195], v[38:39], v[118:119], v[194:195]
	v_pk_add_f32 v[208:209], v[112:113], v[208:209]
	v_pk_add_f32 v[194:195], v[114:115], v[194:195]
	v_mul_f32_e32 v169, 0xbfb8aa3b, v208
	v_mul_f32_e32 v171, 0xbfb8aa3b, v209
	v_exp_f32_e32 v169, v169
	v_exp_f32_e32 v171, v171
	v_add_f32_e32 v169, 1.0, v169
	v_add_f32_e32 v171, 1.0, v171
	v_rcp_f32_e32 v169, v169
	v_rcp_f32_e32 v171, v171
	v_mul_f32_e32 v169, v208, v169
	v_mul_f32_e32 v171, v209, v171
	v_cvt_pk_bf16_f32 v208, v169, v171
	v_mul_f32_e32 v169, 0xbfb8aa3b, v194
	v_mul_f32_e32 v171, 0xbfb8aa3b, v195
	v_exp_f32_e32 v169, v169
	v_exp_f32_e32 v171, v171
	v_add_f32_e32 v169, 1.0, v169
	v_add_f32_e32 v171, 1.0, v171
	v_rcp_f32_e32 v169, v169
	v_rcp_f32_e32 v171, v171
	v_mul_f32_e32 v169, v194, v169
	v_mul_f32_e32 v171, v195, v171
	v_cvt_pk_bf16_f32 v209, v169, v171
	global_store_dwordx2 v[178:179], v[208:209], off offset:256
	v_pk_mul_f32 v[208:209], v[36:37], v[140:141]
	v_pk_mul_f32 v[194:195], v[38:39], v[142:143]
	v_pk_fma_f32 v[208:209], v[44:45], v[136:137], v[208:209]
	v_pk_fma_f32 v[194:195], v[46:47], v[138:139], v[194:195]
	v_pk_fma_f32 v[208:209], v[28:29], v[116:117], v[208:209]
	v_pk_fma_f32 v[194:195], v[30:31], v[118:119], v[194:195]
	v_pk_add_f32 v[208:209], v[112:113], v[208:209]
	v_pk_add_f32 v[194:195], v[114:115], v[194:195]
	v_mul_f32_e32 v169, 0xbfb8aa3b, v208
	v_mul_f32_e32 v171, 0xbfb8aa3b, v209
	v_exp_f32_e32 v169, v169
	v_exp_f32_e32 v171, v171
	v_add_f32_e32 v169, 1.0, v169
	v_add_f32_e32 v171, 1.0, v171
	v_rcp_f32_e32 v169, v169
	v_rcp_f32_e32 v171, v171
	v_mul_f32_e32 v169, v208, v169
	v_mul_f32_e32 v171, v209, v171
	v_cvt_pk_bf16_f32 v208, v169, v171
	v_mul_f32_e32 v169, 0xbfb8aa3b, v194
	v_mul_f32_e32 v171, 0xbfb8aa3b, v195
	v_exp_f32_e32 v169, v169
	v_exp_f32_e32 v171, v171
	v_add_f32_e32 v169, 1.0, v169
	v_add_f32_e32 v171, 1.0, v171
	v_rcp_f32_e32 v169, v169
	v_rcp_f32_e32 v171, v171
	v_mul_f32_e32 v169, v194, v169
	v_mul_f32_e32 v171, v195, v171
; __device__ __forceinline__ unsigned cvt_pk_bf16(float lo, float hi) { unsigned r; asm volatile("v_cvt_pk_bf16_f32 %0, %1, %2" : "=v"(r) : "v"(lo), "v"(hi)); return r; }
; __device__ __forceinline__ float epi_sigmoid(float v) { return __builtin_amdgcn_rcpf(1.0f + __expf(-v)); }
; __device__ __forceinline__ f32x4 dpp_prev4(const f32x4& v) { return (f32x4){dpp_prev(v[0]), dpp_prev(v[1]), dpp_prev(v[2]), dpp_prev(v[3])}; }
; __device__ __forceinline__ f32x4 dpp_next4(const f32x4& v) { return (f32x4){dpp_next(v[0]), dpp_next(v[1]), dpp_next(v[2]), dpp_next(v[3])}; }
;     __device__ __forceinline__ void operator()(const f32x4 (&acc)[2][2][4][2], const Unit& u, int wr, int wc, int fr, int fq) const {
;     ...
;                     for (int kk = 0; kk < 8; ++kk) {
;                         const f32x4 um = (kk == 0) ? dpp_prev4(acc[1][bj][3][n]) : acc[(kk - 1) >> 2][bj][(kk - 1) & 3][n], up = (kk == 7) ? dpp_next4(acc[0][bj][0][n]) : acc[(kk + 1) >> 2][bj][(kk + 1) & 3][n];
;                         const f32x4 c4 = um * w0 + acc[kk >> 2][bj][kk & 3][n] * w1 + up * w2 + bb;
;                         typedef unsigned u32x2_ __attribute__((ext_vector_type(2)));
;                         u32x2_ w; w.x = cvt_pk_bf16(c4[0] * epi_sigmoid(c4[0]), c4[1] * epi_sigmoid(c4[1])); w.y = cvt_pk_bf16(c4[2] * epi_sigmoid(c4[2]), c4[3] * epi_sigmoid(c4[3]));
;                         *(u32x2_*)(xbc + (size_t)(row0 + kk) * 10240 + ch) = w;
;                     }
;                     if (fr == 0) { float* ep = edge + ((size_t)seg * 4 + 0) * 10240 + ch; *(f32x4*)ep = acc[0][bj][0][n]; *(f32x4*)(ep + 10240) = acc[0][bj][1][n]; }
;                     if (fr == 15) { float* ep = edge + ((size_t)seg * 4 + 2) * 10240 + ch; *(f32x4*)ep = acc[1][bj][2][n]; *(f32x4*)(ep + 10240) = acc[1][bj][3][n]; }
	v_cvt_pk_bf16_f32 v209, v169, v171
	global_store_dwordx2 v[180:181], v[208:209], off offset:256
	v_pk_mul_f32 v[208:209], v[28:29], v[140:141]
	v_pk_mul_f32 v[194:195], v[30:31], v[142:143]
	v_pk_fma_f32 v[208:209], v[36:37], v[136:137], v[208:209]
	v_pk_fma_f32 v[194:195], v[38:39], v[138:139], v[194:195]
	v_pk_fma_f32 v[208:209], v[20:21], v[116:117], v[208:209]
	v_pk_fma_f32 v[194:195], v[22:23], v[118:119], v[194:195]
	v_pk_add_f32 v[208:209], v[112:113], v[208:209]
	v_pk_add_f32 v[194:195], v[114:115], v[194:195]
	v_mul_f32_e32 v169, 0xbfb8aa3b, v208
	v_mul_f32_e32 v171, 0xbfb8aa3b, v209
	v_exp_f32_e32 v169, v169
	v_exp_f32_e32 v171, v171
	v_add_f32_e32 v169, 1.0, v169
	v_add_f32_e32 v171, 1.0, v171
	v_rcp_f32_e32 v169, v169
	v_rcp_f32_e32 v171, v171
	v_mul_f32_e32 v169, v208, v169
	v_mul_f32_e32 v171, v209, v171
	v_cvt_pk_bf16_f32 v208, v169, v171
	v_mul_f32_e32 v169, 0xbfb8aa3b, v194
	v_mul_f32_e32 v171, 0xbfb8aa3b, v195
	v_exp_f32_e32 v169, v169
	v_exp_f32_e32 v171, v171
	v_add_f32_e32 v169, 1.0, v169
	v_add_f32_e32 v171, 1.0, v171
	v_rcp_f32_e32 v169, v169
	v_rcp_f32_e32 v171, v171
	v_mul_f32_e32 v169, v194, v169
	v_mul_f32_e32 v171, v195, v171
	v_cvt_pk_bf16_f32 v209, v169, v171
	global_store_dwordx2 v[182:183], v[208:209], off offset:256
	v_pk_mul_f32 v[208:209], v[20:21], v[140:141]
	v_pk_mul_f32 v[194:195], v[22:23], v[142:143]
	v_pk_fma_f32 v[208:209], v[28:29], v[136:137], v[208:209]
	v_pk_fma_f32 v[194:195], v[30:31], v[138:139], v[194:195]
	v_pk_fma_f32 v[208:209], v[12:13], v[116:117], v[208:209]
	v_pk_fma_f32 v[194:195], v[14:15], v[118:119], v[194:195]
	v_pk_add_f32 v[208:209], v[112:113], v[208:209]
	v_pk_add_f32 v[194:195], v[114:115], v[194:195]
	v_mul_f32_e32 v169, 0xbfb8aa3b, v208
	v_mul_f32_e32 v171, 0xbfb8aa3b, v209
	v_exp_f32_e32 v169, v169
	v_exp_f32_e32 v171, v171
	v_add_f32_e32 v169, 1.0, v169
	v_add_f32_e32 v171, 1.0, v171
	v_rcp_f32_e32 v169, v169
	v_rcp_f32_e32 v171, v171
	v_mul_f32_e32 v169, v208, v169
	v_mul_f32_e32 v171, v209, v171
	v_cvt_pk_bf16_f32 v208, v169, v171
	v_mul_f32_e32 v169, 0xbfb8aa3b, v194
	v_mul_f32_e32 v171, 0xbfb8aa3b, v195
	v_exp_f32_e32 v169, v169
	v_exp_f32_e32 v171, v171
	v_add_f32_e32 v169, 1.0, v169
	v_add_f32_e32 v171, 1.0, v171
	v_rcp_f32_e32 v169, v169
	v_rcp_f32_e32 v171, v171
	v_mul_f32_e32 v169, v194, v169
	v_mul_f32_e32 v171, v195, v171
	v_cvt_pk_bf16_f32 v209, v169, v171
	global_store_dwordx2 v[184:185], v[208:209], off offset:256
	v_pk_mul_f32 v[208:209], v[12:13], v[140:141]
	v_pk_mul_f32 v[194:195], v[14:15], v[142:143]
	v_pk_fma_f32 v[208:209], v[20:21], v[136:137], v[208:209]
	v_pk_fma_f32 v[194:195], v[22:23], v[138:139], v[194:195]
	v_pk_fma_f32 v[208:209], v[4:5], v[116:117], v[208:209]
	v_pk_fma_f32 v[194:195], v[6:7], v[118:119], v[194:195]
	v_pk_add_f32 v[208:209], v[112:113], v[208:209]
	v_pk_add_f32 v[194:195], v[114:115], v[194:195]
	v_mul_f32_e32 v169, 0xbfb8aa3b, v208
	v_mul_f32_e32 v171, 0xbfb8aa3b, v209
	v_exp_f32_e32 v169, v169
	v_exp_f32_e32 v171, v171
	v_pk_mul_f32 v[140:141], v[4:5], v[140:141]
	v_pk_mul_f32 v[142:143], v[6:7], v[142:143]
	v_add_f32_e32 v169, 1.0, v169
	v_add_f32_e32 v171, 1.0, v171
	v_rcp_f32_e32 v169, v169
	v_rcp_f32_e32 v171, v171
	v_pk_fma_f32 v[136:137], v[12:13], v[136:137], v[140:141]
	v_pk_fma_f32 v[138:139], v[14:15], v[138:139], v[142:143]
	v_mul_f32_e32 v169, v208, v169
	v_mul_f32_e32 v171, v209, v171
	v_cvt_pk_bf16_f32 v208, v169, v171
	v_mul_f32_e32 v169, 0xbfb8aa3b, v194
	v_mul_f32_e32 v171, 0xbfb8aa3b, v195
	v_exp_f32_e32 v169, v169
	v_exp_f32_e32 v171, v171
	v_add_f32_e32 v169, 1.0, v169
	v_add_f32_e32 v171, 1.0, v171
	v_rcp_f32_e32 v169, v169
	v_rcp_f32_e32 v171, v171
	v_mul_f32_e32 v169, v194, v169
	v_mul_f32_e32 v171, v195, v171
	v_mov_b32_dpp v194, v60 row_shl:1 row_mask:0xf bank_mask:0xf bound_ctrl:1
	v_mov_b32_dpp v195, v61 row_shl:1 row_mask:0xf bank_mask:0xf bound_ctrl:1
	v_pk_fma_f32 v[116:117], v[116:117], v[194:195], v[136:137]
	v_cvt_pk_bf16_f32 v209, v169, v171
	global_store_dwordx2 v[186:187], v[208:209], off offset:256
	v_pk_add_f32 v[112:113], v[112:113], v[116:117]
	v_mov_b32_dpp v208, v62 row_shl:1 row_mask:0xf bank_mask:0xf bound_ctrl:1
	v_mul_f32_e32 v116, 0xbfb8aa3b, v112
	v_exp_f32_e32 v116, v116
	v_mov_b32_dpp v209, v63 row_shl:1 row_mask:0xf bank_mask:0xf bound_ctrl:1
	v_pk_fma_f32 v[118:119], v[118:119], v[208:209], v[138:139]
	v_add_f32_e32 v116, 1.0, v116
	v_rcp_f32_e32 v116, v116
	v_pk_add_f32 v[114:115], v[114:115], v[118:119]
	v_mul_f32_e32 v112, v112, v116
	v_mul_f32_e32 v116, 0xbfb8aa3b, v113
	v_exp_f32_e32 v116, v116
	s_nop 0
	v_add_f32_e32 v116, 1.0, v116
	v_rcp_f32_e32 v116, v116
	s_nop 0
	v_mul_f32_e32 v113, v113, v116
	v_cvt_pk_bf16_f32 v112, v112, v113
	v_mul_f32_e32 v113, 0xbfb8aa3b, v114
	v_exp_f32_e32 v113, v113
	s_nop 0
	v_add_f32_e32 v113, 1.0, v113
	v_rcp_f32_e32 v113, v113
	s_nop 0
	v_mul_f32_e32 v113, v114, v113
	v_mul_f32_e32 v114, 0xbfb8aa3b, v115
	v_exp_f32_e32 v114, v114
	s_nop 0
	v_add_f32_e32 v114, 1.0, v114
	v_rcp_f32_e32 v114, v114
	s_nop 0
	v_mul_f32_e32 v114, v115, v114
	v_cvt_pk_bf16_f32 v113, v113, v114
	global_store_dwordx2 v[188:189], v[112:113], off offset:256
	s_and_saveexec_b64 s[4:5], vcc
	s_xor_b64 s[4:5], exec, s[4:5]
	s_add_u32 s0, s77, s31
	s_addc_u32 s1, s78, s19
	s_add_u32 s40, s0, 0x14000
	s_addc_u32 s41, s1, 0
	s_mov_b64 s[0:1], exec
	s_or_saveexec_b64 s[4:5], s[4:5]
	v_mov_b64_e32 v[114:115], v[6:7]
	v_mov_b64_e32 v[118:119], v[14:15]
	v_mov_b64_e32 v[136:137], s[40:41]
	v_mov_b64_e32 v[112:113], v[4:5]
	v_mov_b64_e32 v[116:117], v[12:13]
	s_xor_b64 exec, exec, s[4:5]
	s_cbranch_execz .LBB0_213
	v_cmp_eq_u32_e32 vcc, 0, v196
	s_mov_b64 s[42:43], s[0:1]
	s_and_saveexec_b64 s[44:45], vcc
	s_add_u32 s40, s77, s31
	s_addc_u32 s41, s78, s19
	s_or_b64 s[42:43], s[0:1], exec
	s_or_b64 exec, exec, s[44:45]
	v_mov_b64_e32 v[136:137], s[40:41]
	s_andn2_b64 s[0:1], s[0:1], exec
	s_and_b64 s[40:41], s[42:43], exec
	v_mov_b64_e32 v[114:115], v[54:55]
	v_mov_b64_e32 v[118:119], v[62:63]
	s_or_b64 s[0:1], s[0:1], s[40:41]
	v_mov_b64_e32 v[112:113], v[52:53]
	v_mov_b64_e32 v[116:117], v[60:61]

; __device__ __forceinline__ unsigned cvt_pk_bf16(float lo, float hi) { unsigned r; asm volatile("v_cvt_pk_bf16_f32 %0, %1, %2" : "=v"(r) : "v"(lo), "v"(hi)); return r; }
; __device__ __forceinline__ float epi_sigmoid(float v) { return __builtin_amdgcn_rcpf(1.0f + __expf(-v)); }
; __device__ __forceinline__ f32x4 dpp_prev4(const f32x4& v) { return (f32x4){dpp_prev(v[0]), dpp_prev(v[1]), dpp_prev(v[2]), dpp_prev(v[3])}; }
; __device__ __forceinline__ f32x4 dpp_next4(const f32x4& v) { return (f32x4){dpp_next(v[0]), dpp_next(v[1]), dpp_next(v[2]), dpp_next(v[3])}; }
;     __device__ __forceinline__ void operator()(const f32x4 (&acc)[2][2][4][2], const Unit& u, int wr, int wc, int fr, int fq) const {
;     ...
;             for (int bj = 0; bj < 2; ++bj)
; #pragma unroll
;                 for (int n = 0; n < 2; ++n) {
;                     const int ch = (pn - 32) * 256 + bj * HALF + cw_ + 4 * n;
;                     const f32x4 w0 = *(const f32x4*)(cw + ch), w1 = *(const f32x4*)(cw + 10240 + ch), w2 = *(const f32x4*)(cw + 2 * 10240 + ch), bb = *(const f32x4*)(cb + ch);
; #pragma unroll
;                     for (int kk = 0; kk < 8; ++kk) {
;                         const f32x4 um = (kk == 0) ? dpp_prev4(acc[1][bj][3][n]) : acc[(kk - 1) >> 2][bj][(kk - 1) & 3][n], up = (kk == 7) ? dpp_next4(acc[0][bj][0][n]) : acc[(kk + 1) >> 2][bj][(kk + 1) & 3][n];
;                         const f32x4 c4 = um * w0 + acc[kk >> 2][bj][kk & 3][n] * w1 + up * w2 + bb;
;                         typedef unsigned u32x2_ __attribute__((ext_vector_type(2)));
;                         u32x2_ w; w.x = cvt_pk_bf16(c4[0] * epi_sigmoid(c4[0]), c4[1] * epi_sigmoid(c4[1])); w.y = cvt_pk_bf16(c4[2] * epi_sigmoid(c4[2]), c4[3] * epi_sigmoid(c4[3]));
;                         *(u32x2_*)(xbc + (size_t)(row0 + kk) * 10240 + ch) = w;
.LBB0_215:
	s_or_b64 exec, exec, s[4:5]
	s_nop 0
	v_or_b32_e32 v112, 0x84, v152
	v_mov_b32_e32 v113, v153
	v_lshlrev_b64 v[112:113], 2, v[112:113]
	v_lshl_add_u64 v[114:115], s[26:27], 0, v[112:113]
	v_lshl_add_u64 v[112:113], s[28:29], 0, v[112:113]
	s_nop 0
	s_waitcnt vmcnt(16)
	v_mov_b32_e32 v136, v212
	v_mov_b32_e32 v137, v213
	v_mov_b32_e32 v138, v214
	v_mov_b32_e32 v139, v215
	v_mov_b32_e32 v140, v216
	v_mov_b32_e32 v141, v217
	v_mov_b32_e32 v142, v218
	v_mov_b32_e32 v143, v219
	v_mov_b32_e32 v116, v220
	v_mov_b32_e32 v117, v221
	v_mov_b32_e32 v118, v222
	v_mov_b32_e32 v119, v223
	v_mov_b32_e32 v112, v224
	v_mov_b32_e32 v113, v225
	v_mov_b32_e32 v114, v226
	v_mov_b32_e32 v115, v227
	v_mov_b32_dpp v174, v0 row_shr:1 row_mask:0xf bank_mask:0xf bound_ctrl:1
	v_mov_b32_dpp v175, v1 row_shr:1 row_mask:0xf bank_mask:0xf bound_ctrl:1
	v_mov_b32_dpp v176, v2 row_shr:1 row_mask:0xf bank_mask:0xf bound_ctrl:1
	v_mov_b32_dpp v177, v3 row_shr:1 row_mask:0xf bank_mask:0xf bound_ctrl:1
	v_cmp_lt_i32_e32 vcc, 14, v196
	s_mov_b64 s[0:1], 0
	v_pk_mul_f32 v[174:175], v[136:137], v[174:175]
	v_pk_mul_f32 v[176:177], v[138:139], v[176:177]
	v_pk_fma_f32 v[174:175], v[56:57], v[140:141], v[174:175]
	v_pk_fma_f32 v[176:177], v[58:59], v[142:143], v[176:177]
	v_pk_fma_f32 v[174:175], v[48:49], v[116:117], v[174:175]
	v_pk_fma_f32 v[176:177], v[50:51], v[118:119], v[176:177]
	v_pk_add_f32 v[174:175], v[112:113], v[174:175]
	v_pk_add_f32 v[176:177], v[114:115], v[176:177]
	v_mul_f32_e32 v169, 0xbfb8aa3b, v174
	v_mul_f32_e32 v171, 0xbfb8aa3b, v175
	v_exp_f32_e32 v169, v169
	v_exp_f32_e32 v171, v171
	v_add_f32_e32 v169, 1.0, v169
	v_add_f32_e32 v171, 1.0, v171
	v_rcp_f32_e32 v169, v169
	v_rcp_f32_e32 v171, v171
	v_mul_f32_e32 v169, v174, v169
	v_mul_f32_e32 v171, v175, v171
	v_cvt_pk_bf16_f32 v174, v169, v171
	v_mul_f32_e32 v169, 0xbfb8aa3b, v176
	v_mul_f32_e32 v171, 0xbfb8aa3b, v177
	v_exp_f32_e32 v169, v169
	v_exp_f32_e32 v171, v171
	v_add_f32_e32 v169, 1.0, v169
	v_add_f32_e32 v171, 1.0, v171
	v_rcp_f32_e32 v169, v169
	v_rcp_f32_e32 v171, v171
	v_mul_f32_e32 v169, v176, v169
	v_mul_f32_e32 v171, v177, v171
	v_pk_mul_f32 v[176:177], v[48:49], v[140:141]
	v_cvt_pk_bf16_f32 v175, v169, v171
	global_store_dwordx2 v[190:191], v[174:175], off offset:264
	v_pk_fma_f32 v[176:177], v[56:57], v[136:137], v[176:177]
	v_pk_mul_f32 v[174:175], v[50:51], v[142:143]
	v_pk_fma_f32 v[176:177], v[40:41], v[116:117], v[176:177]
	v_pk_fma_f32 v[174:175], v[58:59], v[138:139], v[174:175]
	v_pk_add_f32 v[176:177], v[112:113], v[176:177]
	v_pk_fma_f32 v[174:175], v[42:43], v[118:119], v[174:175]
	v_mul_f32_e32 v169, 0xbfb8aa3b, v176
	v_mul_f32_e32 v171, 0xbfb8aa3b, v177
	v_exp_f32_e32 v169, v169
	v_exp_f32_e32 v171, v171
	v_pk_add_f32 v[174:175], v[114:115], v[174:175]
	v_add_f32_e32 v169, 1.0, v169
	v_add_f32_e32 v171, 1.0, v171
	v_rcp_f32_e32 v169, v169
	v_rcp_f32_e32 v171, v171
	v_mul_f32_e32 v169, v176, v169
	v_mul_f32_e32 v171, v177, v171
	v_cvt_pk_bf16_f32 v176, v169, v171
	v_mul_f32_e32 v169, 0xbfb8aa3b, v174
	v_mul_f32_e32 v171, 0xbfb8aa3b, v175
	v_exp_f32_e32 v169, v169
	v_exp_f32_e32 v171, v171
	v_add_f32_e32 v169, 1.0, v169
	v_add_f32_e32 v171, 1.0, v171
	v_rcp_f32_e32 v169, v169
	v_rcp_f32_e32 v171, v171
	v_mul_f32_e32 v169, v174, v169
	v_mul_f32_e32 v171, v175, v171
	v_cvt_pk_bf16_f32 v177, v169, v171
	global_store_dwordx2 v[192:193], v[176:177], off offset:264
	v_pk_mul_f32 v[176:177], v[40:41], v[140:141]
	v_pk_mul_f32 v[174:175], v[42:43], v[142:143]
	v_pk_fma_f32 v[176:177], v[48:49], v[136:137], v[176:177]
	v_pk_fma_f32 v[174:175], v[50:51], v[138:139], v[174:175]
	v_pk_fma_f32 v[176:177], v[32:33], v[116:117], v[176:177]
	v_pk_fma_f32 v[174:175], v[34:35], v[118:119], v[174:175]
	v_pk_add_f32 v[176:177], v[112:113], v[176:177]
	v_pk_add_f32 v[174:175], v[114:115], v[174:175]
	v_mul_f32_e32 v169, 0xbfb8aa3b, v176
	v_mul_f32_e32 v171, 0xbfb8aa3b, v177
	v_exp_f32_e32 v169, v169
	v_exp_f32_e32 v171, v171
	v_add_f32_e32 v169, 1.0, v169
	v_add_f32_e32 v171, 1.0, v171
	v_rcp_f32_e32 v169, v169
	v_rcp_f32_e32 v171, v171
	v_mul_f32_e32 v169, v176, v169
	v_mul_f32_e32 v171, v177, v171
	v_cvt_pk_bf16_f32 v176, v169, v171
	v_mul_f32_e32 v169, 0xbfb8aa3b, v174
	v_mul_f32_e32 v171, 0xbfb8aa3b, v175
	v_exp_f32_e32 v169, v169
	v_exp_f32_e32 v171, v171
	v_add_f32_e32 v169, 1.0, v169
	v_add_f32_e32 v171, 1.0, v171
	v_rcp_f32_e32 v169, v169
	v_rcp_f32_e32 v171, v171
	v_mul_f32_e32 v169, v174, v169
	v_mul_f32_e32 v171, v175, v171
	v_cvt_pk_bf16_f32 v177, v169, v171
	global_store_dwordx2 v[178:179], v[176:177], off offset:264
	v_pk_mul_f32 v[176:177], v[32:33], v[140:141]
	v_pk_mul_f32 v[174:175], v[34:35], v[142:143]
	v_pk_fma_f32 v[176:177], v[40:41], v[136:137], v[176:177]
	v_pk_fma_f32 v[174:175], v[42:43], v[138:139], v[174:175]
	v_pk_fma_f32 v[176:177], v[24:25], v[116:117], v[176:177]
	v_pk_fma_f32 v[174:175], v[26:27], v[118:119], v[174:175]
	v_pk_add_f32 v[176:177], v[112:113], v[176:177]
	v_pk_add_f32 v[174:175], v[114:115], v[174:175]
	v_mul_f32_e32 v169, 0xbfb8aa3b, v176
	v_mul_f32_e32 v171, 0xbfb8aa3b, v177
	v_exp_f32_e32 v169, v169
	v_exp_f32_e32 v171, v171
	v_add_f32_e32 v169, 1.0, v169
	v_add_f32_e32 v171, 1.0, v171
	v_rcp_f32_e32 v169, v169
	v_rcp_f32_e32 v171, v171
	v_mul_f32_e32 v169, v176, v169
	v_mul_f32_e32 v171, v177, v171
	v_cvt_pk_bf16_f32 v176, v169, v171
	v_mul_f32_e32 v169, 0xbfb8aa3b, v174
	v_mul_f32_e32 v171, 0xbfb8aa3b, v175
	v_exp_f32_e32 v169, v169
	v_exp_f32_e32 v171, v171
	v_add_f32_e32 v169, 1.0, v169
	v_add_f32_e32 v171, 1.0, v171
	v_rcp_f32_e32 v169, v169
	v_rcp_f32_e32 v171, v171
	v_mul_f32_e32 v169, v174, v169
	v_mul_f32_e32 v171, v175, v171
; __device__ __forceinline__ unsigned cvt_pk_bf16(float lo, float hi) { unsigned r; asm volatile("v_cvt_pk_bf16_f32 %0, %1, %2" : "=v"(r) : "v"(lo), "v"(hi)); return r; }
; __device__ __forceinline__ float epi_sigmoid(float v) { return __builtin_amdgcn_rcpf(1.0f + __expf(-v)); }
; __device__ __forceinline__ f32x4 dpp_prev4(const f32x4& v) { return (f32x4){dpp_prev(v[0]), dpp_prev(v[1]), dpp_prev(v[2]), dpp_prev(v[3])}; }
; __device__ __forceinline__ f32x4 dpp_next4(const f32x4& v) { return (f32x4){dpp_next(v[0]), dpp_next(v[1]), dpp_next(v[2]), dpp_next(v[3])}; }
;     __device__ __forceinline__ void operator()(const f32x4 (&acc)[2][2][4][2], const Unit& u, int wr, int wc, int fr, int fq) const {
;     ...
;                     for (int kk = 0; kk < 8; ++kk) {
;                         const f32x4 um = (kk == 0) ? dpp_prev4(acc[1][bj][3][n]) : acc[(kk - 1) >> 2][bj][(kk - 1) & 3][n], up = (kk == 7) ? dpp_next4(acc[0][bj][0][n]) : acc[(kk + 1) >> 2][bj][(kk + 1) & 3][n];
;                         const f32x4 c4 = um * w0 + acc[kk >> 2][bj][kk & 3][n] * w1 + up * w2 + bb;
;                         typedef unsigned u32x2_ __attribute__((ext_vector_type(2)));
;                         u32x2_ w; w.x = cvt_pk_bf16(c4[0] * epi_sigmoid(c4[0]), c4[1] * epi_sigmoid(c4[1])); w.y = cvt_pk_bf16(c4[2] * epi_sigmoid(c4[2]), c4[3] * epi_sigmoid(c4[3]));
;                         *(u32x2_*)(xbc + (size_t)(row0 + kk) * 10240 + ch) = w;
;                     }
;                     if (fr == 0) { float* ep = edge + ((size_t)seg * 4 + 0) * 10240 + ch; *(f32x4*)ep = acc[0][bj][0][n]; *(f32x4*)(ep + 10240) = acc[0][bj][1][n]; }
;                     if (fr == 15) { float* ep = edge + ((size_t)seg * 4 + 2) * 10240 + ch; *(f32x4*)ep = acc[1][bj][2][n]; *(f32x4*)(ep + 10240) = acc[1][bj][3][n]; }
	v_cvt_pk_bf16_f32 v177, v169, v171
	global_store_dwordx2 v[180:181], v[176:177], off offset:264
	v_pk_mul_f32 v[176:177], v[24:25], v[140:141]
	v_pk_mul_f32 v[174:175], v[26:27], v[142:143]
	v_pk_fma_f32 v[176:177], v[32:33], v[136:137], v[176:177]
	v_pk_fma_f32 v[174:175], v[34:35], v[138:139], v[174:175]
	v_pk_fma_f32 v[176:177], v[16:17], v[116:117], v[176:177]
	v_pk_fma_f32 v[174:175], v[18:19], v[118:119], v[174:175]
	v_pk_add_f32 v[176:177], v[112:113], v[176:177]
	v_pk_add_f32 v[174:175], v[114:115], v[174:175]
	v_mul_f32_e32 v169, 0xbfb8aa3b, v176
	v_mul_f32_e32 v171, 0xbfb8aa3b, v177
	v_exp_f32_e32 v169, v169
	v_exp_f32_e32 v171, v171
	v_add_f32_e32 v169, 1.0, v169
	v_add_f32_e32 v171, 1.0, v171
	v_rcp_f32_e32 v169, v169
	v_rcp_f32_e32 v171, v171
	v_mul_f32_e32 v169, v176, v169
	v_mul_f32_e32 v171, v177, v171
	v_cvt_pk_bf16_f32 v176, v169, v171
	v_mul_f32_e32 v169, 0xbfb8aa3b, v174
	v_mul_f32_e32 v171, 0xbfb8aa3b, v175
	v_exp_f32_e32 v169, v169
	v_exp_f32_e32 v171, v171
	v_add_f32_e32 v169, 1.0, v169
	v_add_f32_e32 v171, 1.0, v171
	v_rcp_f32_e32 v169, v169
	v_rcp_f32_e32 v171, v171
	v_mul_f32_e32 v169, v174, v169
	v_mul_f32_e32 v171, v175, v171
	v_cvt_pk_bf16_f32 v177, v169, v171
	global_store_dwordx2 v[182:183], v[176:177], off offset:264
	v_pk_mul_f32 v[176:177], v[16:17], v[140:141]
	v_pk_mul_f32 v[174:175], v[18:19], v[142:143]
	v_pk_fma_f32 v[176:177], v[24:25], v[136:137], v[176:177]
	v_pk_fma_f32 v[174:175], v[26:27], v[138:139], v[174:175]
	v_pk_fma_f32 v[176:177], v[8:9], v[116:117], v[176:177]
	v_pk_fma_f32 v[174:175], v[10:11], v[118:119], v[174:175]
	v_pk_add_f32 v[176:177], v[112:113], v[176:177]
	v_pk_add_f32 v[174:175], v[114:115], v[174:175]
	v_mul_f32_e32 v169, 0xbfb8aa3b, v176
	v_mul_f32_e32 v171, 0xbfb8aa3b, v177
	v_exp_f32_e32 v169, v169
	v_exp_f32_e32 v171, v171
	v_add_f32_e32 v169, 1.0, v169
	v_add_f32_e32 v171, 1.0, v171
	v_rcp_f32_e32 v169, v169
	v_rcp_f32_e32 v171, v171
	v_mul_f32_e32 v169, v176, v169
	v_mul_f32_e32 v171, v177, v171
	v_cvt_pk_bf16_f32 v176, v169, v171
	v_mul_f32_e32 v169, 0xbfb8aa3b, v174
	v_mul_f32_e32 v171, 0xbfb8aa3b, v175
	v_exp_f32_e32 v169, v169
	v_exp_f32_e32 v171, v171
	v_add_f32_e32 v169, 1.0, v169
	v_add_f32_e32 v171, 1.0, v171
	v_rcp_f32_e32 v169, v169
	v_rcp_f32_e32 v171, v171
	v_mul_f32_e32 v169, v174, v169
	v_mul_f32_e32 v171, v175, v171
	v_cvt_pk_bf16_f32 v177, v169, v171
	global_store_dwordx2 v[184:185], v[176:177], off offset:264
	v_pk_mul_f32 v[176:177], v[8:9], v[140:141]
	v_pk_mul_f32 v[174:175], v[10:11], v[142:143]
	v_pk_fma_f32 v[176:177], v[16:17], v[136:137], v[176:177]
	v_pk_fma_f32 v[174:175], v[18:19], v[138:139], v[174:175]
	v_pk_fma_f32 v[176:177], v[0:1], v[116:117], v[176:177]
	v_pk_fma_f32 v[174:175], v[2:3], v[118:119], v[174:175]
	v_pk_add_f32 v[176:177], v[112:113], v[176:177]
	v_pk_add_f32 v[174:175], v[114:115], v[174:175]
	v_mul_f32_e32 v169, 0xbfb8aa3b, v176
	v_mul_f32_e32 v171, 0xbfb8aa3b, v177
	v_exp_f32_e32 v169, v169
	v_exp_f32_e32 v171, v171
	v_pk_mul_f32 v[140:141], v[0:1], v[140:141]
	v_pk_mul_f32 v[142:143], v[2:3], v[142:143]
	v_add_f32_e32 v169, 1.0, v169
	v_add_f32_e32 v171, 1.0, v171
	v_rcp_f32_e32 v169, v169
	v_rcp_f32_e32 v171, v171
	v_pk_fma_f32 v[136:137], v[8:9], v[136:137], v[140:141]
	v_pk_fma_f32 v[138:139], v[10:11], v[138:139], v[142:143]
	v_mul_f32_e32 v169, v176, v169
	v_mul_f32_e32 v171, v177, v171
	v_cvt_pk_bf16_f32 v176, v169, v171
	v_mul_f32_e32 v169, 0xbfb8aa3b, v174
	v_mul_f32_e32 v171, 0xbfb8aa3b, v175
	v_exp_f32_e32 v169, v169
	v_exp_f32_e32 v171, v171
	v_add_f32_e32 v169, 1.0, v169
	v_add_f32_e32 v171, 1.0, v171
	v_rcp_f32_e32 v169, v169
	v_rcp_f32_e32 v171, v171
	v_mul_f32_e32 v169, v174, v169
	v_mul_f32_e32 v171, v175, v171
	v_mov_b32_dpp v174, v56 row_shl:1 row_mask:0xf bank_mask:0xf bound_ctrl:1
	v_mov_b32_dpp v175, v57 row_shl:1 row_mask:0xf bank_mask:0xf bound_ctrl:1
	v_pk_fma_f32 v[116:117], v[116:117], v[174:175], v[136:137]
	v_cvt_pk_bf16_f32 v177, v169, v171
	global_store_dwordx2 v[186:187], v[176:177], off offset:264
	v_pk_add_f32 v[112:113], v[112:113], v[116:117]
	v_mov_b32_dpp v176, v58 row_shl:1 row_mask:0xf bank_mask:0xf bound_ctrl:1
	v_mul_f32_e32 v116, 0xbfb8aa3b, v112
	v_exp_f32_e32 v116, v116
	v_mov_b32_dpp v177, v59 row_shl:1 row_mask:0xf bank_mask:0xf bound_ctrl:1
	v_pk_fma_f32 v[118:119], v[118:119], v[176:177], v[138:139]
	v_add_f32_e32 v116, 1.0, v116
	v_rcp_f32_e32 v116, v116
	v_pk_add_f32 v[114:115], v[114:115], v[118:119]
	v_mul_f32_e32 v112, v112, v116
	v_mul_f32_e32 v116, 0xbfb8aa3b, v113
	v_exp_f32_e32 v116, v116
	s_nop 0
	v_add_f32_e32 v116, 1.0, v116
	v_rcp_f32_e32 v116, v116
	s_nop 0
	v_mul_f32_e32 v113, v113, v116
	v_cvt_pk_bf16_f32 v112, v112, v113
	v_mul_f32_e32 v113, 0xbfb8aa3b, v114
	v_exp_f32_e32 v113, v113
	s_nop 0
	v_add_f32_e32 v113, 1.0, v113
	v_rcp_f32_e32 v113, v113
	s_nop 0
	v_mul_f32_e32 v113, v114, v113
	v_mul_f32_e32 v114, 0xbfb8aa3b, v115
	v_exp_f32_e32 v114, v114
	s_nop 0
	v_add_f32_e32 v114, 1.0, v114
	v_rcp_f32_e32 v114, v114
	s_nop 0
	v_mul_f32_e32 v114, v115, v114
	v_cvt_pk_bf16_f32 v113, v113, v114
	global_store_dwordx2 v[188:189], v[112:113], off offset:264
	s_and_saveexec_b64 s[4:5], vcc
	s_xor_b64 s[4:5], exec, s[4:5]
	s_add_u32 s0, s77, s31
	s_addc_u32 s1, s78, s19
	s_add_u32 s40, s0, 0x14000
	s_addc_u32 s41, s1, 0
	s_mov_b64 s[0:1], exec
	s_or_saveexec_b64 s[4:5], s[4:5]
	v_mov_b64_e32 v[114:115], v[2:3]
	v_mov_b64_e32 v[118:119], v[10:11]
	v_mov_b64_e32 v[136:137], s[40:41]
	v_mov_b64_e32 v[112:113], v[0:1]
	v_mov_b64_e32 v[116:117], v[8:9]
	s_xor_b64 exec, exec, s[4:5]
	s_cbranch_execz .LBB0_221
	v_cmp_eq_u32_e32 vcc, 0, v196
	s_mov_b64 s[42:43], s[0:1]
	s_and_saveexec_b64 s[44:45], vcc
	s_add_u32 s40, s77, s31
	s_addc_u32 s41, s78, s19
	s_or_b64 s[42:43], s[0:1], exec
	s_or_b64 exec, exec, s[44:45]
	v_mov_b64_e32 v[136:137], s[40:41]
	s_andn2_b64 s[0:1], s[0:1], exec
	s_and_b64 s[40:41], s[42:43], exec
	v_mov_b64_e32 v[114:115], v[50:51]
	v_mov_b64_e32 v[118:119], v[58:59]
	s_or_b64 s[0:1], s[0:1], s[40:41]
	v_mov_b64_e32 v[112:113], v[48:49]
	v_mov_b64_e32 v[116:117], v[56:57]

; __device__ __forceinline__ int crow(int r, int hi) { return (r & 3) + 8 * (r >> 2) + 4 * hi; }
; __device__ __forceinline__ unsigned cvtpk(float lo, float hi) { unsigned r; asm volatile("v_cvt_pk_bf16_f32 %0, %1, %2" : "=v"(r) : "v"(lo), "v"(hi)); return r; }
; __device__ __forceinline__ void attn_dense_body(AttnPre& P, const bf16* __restrict__ Kh, const bf16* __restrict__ Vh, bf16* Ob, int seq, char* lds, const float* qnw, const float* rtab, int t0, int tid_in, ...
;     ...
;   if (hi == 0) li_l[r32] = l_reg; asm volatile("s_waitcnt lgkmcnt(0)" ::: "memory");
;   float rli[16];
; #pragma unroll
;   for (int r = 0; r < 16; ++r) rli[r] = __builtin_amdgcn_rcpf(li_l[crow(r, hi)]);
;   bf16* Ow = Ob + (long)(wid * QBLK) * LDO;
; #pragma unroll
;   for (int r = 0; r < 16; ++r) { int orow = crow(r, hi);
; #pragma unroll
;     for (int d0 = 0; d0 < 4; ++d0) Ow[(long)orow * LDO + d0 * 32 + r32] = (bf16)(cvtpk(o[d0][r] * rli[r], 0.f) & 0xffffu); }
.LBB0_767:
	s_or_b64 exec, exec, s[6:7]
	s_waitcnt lgkmcnt(0)
	v_add_u32_e32 v72, s37, v222
	ds_read_b128 v[80:83], v72
	ds_read_b128 v[84:87], v72 offset:32
	ds_read_b128 v[88:91], v72 offset:64
	ds_read_b128 v[92:95], v72 offset:96
	s_lshl_b64 s[0:1], s[0:1], 1
	s_add_u32 s6, s51, s0
	s_addc_u32 s7, s52, s1
	s_ashr_i32 s37, s36, 31
	s_lshl_b64 s[0:1], s[36:37], 13
	s_add_u32 s0, s6, s0
	s_addc_u32 s1, s7, s1
	s_lshl_b32 vcc_lo, s36, 8
	s_add_i32 vcc_lo, vcc_lo, 0x11000
	s_waitcnt lgkmcnt(0)
	v_rcp_f32_e32 v64, v80
	v_rcp_f32_e32 v65, v81
	v_rcp_f32_e32 v66, v82
	v_rcp_f32_e32 v67, v83
	v_rcp_f32_e32 v68, v84
	v_rcp_f32_e32 v69, v85
	v_rcp_f32_e32 v70, v86
	v_rcp_f32_e32 v71, v87
	v_rcp_f32_e32 v72, v88
	v_rcp_f32_e32 v73, v89
	v_rcp_f32_e32 v74, v90
	v_rcp_f32_e32 v75, v91
	v_rcp_f32_e32 v76, v92
	v_rcp_f32_e32 v77, v93
	v_rcp_f32_e32 v78, v94
	v_rcp_f32_e32 v79, v95
	v_mbcnt_lo_u32_b32 v80, -1, 0
	v_mbcnt_hi_u32_b32 v80, -1, v80
	v_lshl_add_u32 v81, v176, 6, vcc_lo
	v_bfe_u32 v82, v176, 1, 3
	v_lshrrev_b32_e32 v83, 4, v222
	v_add_u32_e32 v84, 0, v83
	v_xor_b32_e32 v84, v84, v82
	v_lshl_add_u32 v84, v84, 3, v81
	v_add_u32_e32 v85, 2, v83
	v_xor_b32_e32 v85, v85, v82
	v_lshl_add_u32 v85, v85, 3, v81
	v_add_u32_e32 v86, 4, v83
	v_xor_b32_e32 v86, v86, v82
	v_lshl_add_u32 v86, v86, 3, v81
	v_add_u32_e32 v87, 6, v83
	v_xor_b32_e32 v87, v87, v82
	v_lshl_add_u32 v87, v87, 3, v81
	v_lshrrev_b32_e32 v88, 5, v80
	v_bfe_u32 v89, v80, 2, 2
	v_and_b32_e32 v90, 3, v80
	v_bfe_u32 v91, v80, 4, 1
	v_lshl_add_u32 v92, v88, 3, v89
	v_lshl_add_u32 v93, v91, 2, v90
	v_lshrrev_b32_e32 v94, 1, v89
	v_lshl_add_u32 v94, v88, 2, v94
	v_xor_b32_e32 v81, v93, v94
	v_lshlrev_b32_e32 v81, 3, v81
	v_lshl_add_u32 v81, v92, 6, v81
	v_add_u32_e32 v81, vcc_lo, v81
	v_add_u32_e32 v94, 2, v94
	v_xor_b32_e32 v82, v93, v94
	v_lshlrev_b32_e32 v82, 3, v82
	v_add_u32_e32 v92, 4, v92
	v_lshl_add_u32 v82, v92, 6, v82
	v_add_u32_e32 v82, vcc_lo, v82
	v_and_b32_e32 v92, 15, v80
	v_lshl_add_u32 v92, v91, 4, v92
	v_lshlrev_b32_e32 v92, 13, v92
	v_lshl_add_u32 v92, v88, 4, v92
	v_mov_b32_e32 v93, 0
	v_lshl_add_u64 v[92:93], s[0:1], 0, v[92:93]
	v_mul_f32_e32 v0, v0, v64
	v_mul_f32_e32 v1, v1, v65
	v_mul_f32_e32 v2, v2, v66
	v_mul_f32_e32 v3, v3, v67
	v_cvt_pk_bf16_f32 v0, v0, v1
	v_cvt_pk_bf16_f32 v1, v2, v3
	ds_write_b64 v84, v[0:1]
	v_mul_f32_e32 v4, v4, v68
	v_mul_f32_e32 v5, v5, v69
	v_mul_f32_e32 v6, v6, v70
	v_mul_f32_e32 v7, v7, v71
	v_cvt_pk_bf16_f32 v4, v4, v5
	v_cvt_pk_bf16_f32 v5, v6, v7
	ds_write_b64 v85, v[4:5]
	v_mul_f32_e32 v8, v8, v72
	v_mul_f32_e32 v9, v9, v73
	v_mul_f32_e32 v10, v10, v74
	v_mul_f32_e32 v11, v11, v75
	v_cvt_pk_bf16_f32 v8, v8, v9
	v_cvt_pk_bf16_f32 v9, v10, v11
	ds_write_b64 v86, v[8:9]
	v_mul_f32_e32 v12, v12, v76
	v_mul_f32_e32 v13, v13, v77
	v_mul_f32_e32 v14, v14, v78
	v_mul_f32_e32 v15, v15, v79
	v_cvt_pk_bf16_f32 v12, v12, v13
	v_cvt_pk_bf16_f32 v13, v14, v15
	ds_write_b64 v87, v[12:13]
	v_mul_f32_e32 v48, v48, v64
	v_mul_f32_e32 v49, v49, v65
	v_mul_f32_e32 v50, v50, v66
	v_mul_f32_e32 v51, v51, v67
	v_cvt_pk_bf16_f32 v48, v48, v49
	v_cvt_pk_bf16_f32 v49, v50, v51
	ds_write_b64 v84, v[48:49] offset:2048
	v_mul_f32_e32 v52, v52, v68
	v_mul_f32_e32 v53, v53, v69
	v_mul_f32_e32 v54, v54, v70
	v_mul_f32_e32 v55, v55, v71
	v_cvt_pk_bf16_f32 v52, v52, v53
	v_cvt_pk_bf16_f32 v53, v54, v55
	ds_write_b64 v85, v[52:53] offset:2048
	v_mul_f32_e32 v56, v56, v72
	v_mul_f32_e32 v57, v57, v73
	v_mul_f32_e32 v58, v58, v74
	v_mul_f32_e32 v59, v59, v75
	v_cvt_pk_bf16_f32 v56, v56, v57
	v_cvt_pk_bf16_f32 v57, v58, v59
	ds_write_b64 v86, v[56:57] offset:2048
	v_mul_f32_e32 v60, v60, v76
	v_mul_f32_e32 v61, v61, v77
	v_mul_f32_e32 v62, v62, v78
	v_mul_f32_e32 v63, v63, v79
	v_cvt_pk_bf16_f32 v60, v60, v61
	v_cvt_pk_bf16_f32 v61, v62, v63
	ds_write_b64 v87, v[60:61] offset:2048
	v_mul_f32_e32 v32, v32, v64
	v_mul_f32_e32 v33, v33, v65
	v_mul_f32_e32 v34, v34, v66
	v_mul_f32_e32 v35, v35, v67
	v_cvt_pk_bf16_f32 v32, v32, v33
	v_cvt_pk_bf16_f32 v33, v34, v35
	ds_write_b64 v84, v[32:33] offset:4096
	v_mul_f32_e32 v36, v36, v68
	v_mul_f32_e32 v37, v37, v69
	v_mul_f32_e32 v38, v38, v70
	v_mul_f32_e32 v39, v39, v71
	v_cvt_pk_bf16_f32 v36, v36, v37
	v_cvt_pk_bf16_f32 v37, v38, v39
	ds_write_b64 v85, v[36:37] offset:4096
	v_mul_f32_e32 v40, v40, v72
	v_mul_f32_e32 v41, v41, v73
	v_mul_f32_e32 v42, v42, v74
	v_mul_f32_e32 v43, v43, v75
	v_cvt_pk_bf16_f32 v40, v40, v41
	v_cvt_pk_bf16_f32 v41, v42, v43
	ds_write_b64 v86, v[40:41] offset:4096
	v_mul_f32_e32 v44, v44, v76
	v_mul_f32_e32 v45, v45, v77
	v_mul_f32_e32 v46, v46, v78
	v_mul_f32_e32 v47, v47, v79
	v_cvt_pk_bf16_f32 v44, v44, v45
	v_cvt_pk_bf16_f32 v45, v46, v47
	ds_write_b64 v87, v[44:45] offset:4096
	v_mul_f32_e32 v16, v16, v64
	v_mul_f32_e32 v17, v17, v65
	v_mul_f32_e32 v18, v18, v66
	v_mul_f32_e32 v19, v19, v67
	v_cvt_pk_bf16_f32 v16, v16, v17
	v_cvt_pk_bf16_f32 v17, v18, v19
	ds_write_b64 v84, v[16:17] offset:6144
	v_mul_f32_e32 v20, v20, v68
	v_mul_f32_e32 v21, v21, v69
	v_mul_f32_e32 v22, v22, v70
	v_mul_f32_e32 v23, v23, v71
	v_cvt_pk_bf16_f32 v20, v20, v21
	v_cvt_pk_bf16_f32 v21, v22, v23
	ds_write_b64 v85, v[20:21] offset:6144
	v_mul_f32_e32 v24, v24, v72
	v_mul_f32_e32 v25, v25, v73
	v_mul_f32_e32 v26, v26, v74
	v_mul_f32_e32 v27, v27, v75
	v_cvt_pk_bf16_f32 v24, v24, v25
	v_cvt_pk_bf16_f32 v25, v26, v27
	ds_write_b64 v86, v[24:25] offset:6144
	v_mul_f32_e32 v28, v28, v76
	v_mul_f32_e32 v29, v29, v77
	v_mul_f32_e32 v30, v30, v78
	v_mul_f32_e32 v31, v31, v79
	v_cvt_pk_bf16_f32 v28, v28, v29
	v_cvt_pk_bf16_f32 v29, v30, v31
	ds_write_b64 v87, v[28:29] offset:6144
	s_waitcnt lgkmcnt(0)
; __device__ __forceinline__ int crow(int r, int hi) { return (r & 3) + 8 * (r >> 2) + 4 * hi; }
; __device__ __forceinline__ unsigned cvtpk(float lo, float hi) { unsigned r; asm volatile("v_cvt_pk_bf16_f32 %0, %1, %2" : "=v"(r) : "v"(lo), "v"(hi)); return r; }
; __device__ __forceinline__ void attn_dense_body(AttnPre& P, const bf16* __restrict__ Kh, const bf16* __restrict__ Vh, bf16* Ob, int seq, char* lds, const float* qnw, const float* rtab, int t0, int tid_in, ...
;     ...
;   if (hi == 0) li_l[r32] = l_reg; asm volatile("s_waitcnt lgkmcnt(0)" ::: "memory");
;   float rli[16];
; #pragma unroll
;   for (int r = 0; r < 16; ++r) rli[r] = __builtin_amdgcn_rcpf(li_l[crow(r, hi)]);
;   bf16* Ow = Ob + (long)(wid * QBLK) * LDO;
; #pragma unroll
;   for (int r = 0; r < 16; ++r) { int orow = crow(r, hi);
; #pragma unroll
;     for (int d0 = 0; d0 < 4; ++d0) Ow[(long)orow * LDO + d0 * 32 + r32] = (bf16)(cvtpk(o[d0][r] * rli[r], 0.f) & 0xffffu); }
	ds_read_b64_tr_b16 v[0:1], v81
	ds_read_b64_tr_b16 v[2:3], v82
	ds_read_b64_tr_b16 v[4:5], v81 offset:1024
	ds_read_b64_tr_b16 v[6:7], v82 offset:1024
	ds_read_b64_tr_b16 v[8:9], v81 offset:2048
	ds_read_b64_tr_b16 v[10:11], v82 offset:2048
	ds_read_b64_tr_b16 v[12:13], v81 offset:3072
	ds_read_b64_tr_b16 v[14:15], v82 offset:3072
	ds_read_b64_tr_b16 v[16:17], v81 offset:4096
	ds_read_b64_tr_b16 v[18:19], v82 offset:4096
	ds_read_b64_tr_b16 v[20:21], v81 offset:5120
	ds_read_b64_tr_b16 v[22:23], v82 offset:5120
	ds_read_b64_tr_b16 v[24:25], v81 offset:6144
	ds_read_b64_tr_b16 v[26:27], v82 offset:6144
	ds_read_b64_tr_b16 v[28:29], v81 offset:7168
	ds_read_b64_tr_b16 v[30:31], v82 offset:7168
	s_waitcnt lgkmcnt(14)
	global_store_dwordx4 v[92:93], v[0:3], off
	s_waitcnt lgkmcnt(12)
	global_store_dwordx4 v[92:93], v[4:7], off offset:32
	s_waitcnt lgkmcnt(10)
	global_store_dwordx4 v[92:93], v[8:11], off offset:64
	s_waitcnt lgkmcnt(8)
	global_store_dwordx4 v[92:93], v[12:15], off offset:96
	s_waitcnt lgkmcnt(6)
	global_store_dwordx4 v[92:93], v[16:19], off offset:128
	s_waitcnt lgkmcnt(4)
	global_store_dwordx4 v[92:93], v[20:23], off offset:160
	s_waitcnt lgkmcnt(2)
	global_store_dwordx4 v[92:93], v[24:27], off offset:192
	s_waitcnt lgkmcnt(0)
	global_store_dwordx4 v[92:93], v[28:31], off offset:224
	s_movk_i32 s0, 0x4000
	s_mov_b64 s[0:1], s[28:29]
	s_mov_b64 s[6:7], s[30:31]
	s_and_b64 vcc, exec, s[34:35]
	s_nop 1
	v_mov_b32_e32 v0, v239
	s_cbranch_vccnz .LBB0_796
